# strategy 9 extended: scalar address-select block rotated off the K-loop head in all six GEMM loops
# baseline (speedup 1.0000x reference)
; #define PG8_STAGE(bufoff, gbase, voff) do { _Pragma("unroll") for (int _i = 0; _i < 2; ++_i) \
;         __builtin_amdgcn_global_load_lds((const unsigned*)((const char*)(gbase) + (voff)[_i]), (LAS unsigned*)(lds + (bufoff) + ldsw + _i * 8192), 16, 0, 0); } while (0)
; #define PG8_LDA(dst, b, h) do { _Pragma("unroll") for (int m = 0; m < 4; ++m) _Pragma("unroll") for (int k = 0; k < 2; ++k) dst[m][k] = *(const LAS bf16x8*)(lds + PG8_SA(b, h) + aoff + m * 2048 + k * 1024); } while (0)
; #define PG8_LDB(dst, b, h) do { _Pragma("unroll") for (int n = 0; n < 2; ++n) _Pragma("unroll") for (int k = 0; k < 2; ++k) dst[n][k] = *(const LAS bf16x8*)(lds + PG8_SB(b, h) + boff + n * 2048 + k * 1024); } while (0)
; #define PG8_WAIT_V(n) asm volatile("s_waitcnt vmcnt(" #n ")" ::: "memory")
; #define PG8_WAIT_L(n) asm volatile("s_waitcnt lgkmcnt(" #n ")" ::: "memory")
; #define PG8_BAR __builtin_amdgcn_s_barrier()
; #define PG8_SCHED __builtin_amdgcn_sched_barrier(0)
; template <class Epi, class Sched, bool ALIGN_EPI = false, bool SP2 = false>
; __device__ __forceinline__ void gemm_phase(LAS unsigned char* lds, const Gemm g, const Sched& S, const Epi& E, const int tid_) {
;     ...
;         const char* nA = has_next ? (const char*)g.A + (size_t)nxt.pm * tstep : cA; const char* nB = has_next ? (const char*)g.Bt + (size_t)nxt.pn * tstep : cB;
;         for (int t = 0; t < nt; t += 2) {
;             const bool last = (t == nt - 2);
;             const char* a1 = cA + (size_t)(t + 1) * kstep;
;             const char* a2 = last ? nA : cA + (size_t)(t + 2) * kstep; const char* b2 = last ? nB : cB + (size_t)(t + 2) * kstep;
;             const char* a3 = a2 + kstep; const char* b3 = b2 + kstep;
;             if (last && has_next) S.a_ready(nxt);
;             if constexpr (SP2) {
;             PG8_LDB(B0, 0, 0); PG8_LDB(B1, 0, 1); PG8_SCHED; PG8_LDA(At, 0, 0); PG8_STAGE(PG8_SA(1, 1), a1 + hstep, voffA);
;             PG8_WAIT_V(8); PG8_WAIT_L(0); PG8_BAR; PG8_MMA(0, 0, At, B0); PG8_MMA(0, 1, At, B1); PG8_BAR; PG8_SCHED;
;     ...
;         for (int a = 0; a < 2; ++a)
; #pragma unroll
;             for (int b = 0; b < 2; ++b)
; #pragma unroll
;                 for (int m = 0; m < 4; ++m)
; #pragma unroll
;                     for (int n = 0; n < 2; ++n) acc[a][b][m][n] = (f32x4){0.f, 0.f, 0.f, 0.f};
;         cur = nxt; cA = nA; cB = nB; ++ui;
.LBB0_69:
	s_ashr_i32 s17, s16, 31
	s_lshl_b64 s[18:19], s[16:17], 20
	s_add_u32 s18, s29, s18
	s_addc_u32 s19, s30, s19
	s_and_b64 s[42:43], s[40:41], exec
	s_cselect_b32 s17, s19, s47
	s_cselect_b32 s21, s18, s46
	s_ashr_i32 s15, s14, 31
	s_lshl_b64 s[42:43], s[14:15], 20
	s_add_u32 s42, s31, s42
	s_addc_u32 s43, s56, s43
	s_and_b64 s[50:51], s[40:41], exec
	s_cselect_b32 s15, s43, s49
	s_cselect_b32 s66, s42, s48
	s_add_u32 s67, s48, 0x100
	v_mov_b32_e32 v2, 0
	s_addc_u32 s68, s49, 0
	s_mov_b32 s69, -2
	v_mov_b32_e32 v3, v2
	v_mov_b64_e32 v[4:5], 0
	v_mov_b64_e32 v[6:7], 0
	v_mov_b64_e32 v[8:9], 0
	v_mov_b64_e32 v[10:11], 0
	v_mov_b64_e32 v[12:13], 0
	v_mov_b64_e32 v[14:15], 0
	v_mov_b64_e32 v[16:17], 0
	v_mov_b64_e32 v[18:19], 0
	v_mov_b64_e32 v[20:21], 0
	v_mov_b64_e32 v[22:23], 0
	v_mov_b64_e32 v[24:25], 0
	v_mov_b64_e32 v[26:27], 0
	v_mov_b64_e32 v[28:29], 0
	v_mov_b64_e32 v[30:31], 0
	v_mov_b64_e32 v[32:33], 0
	v_mov_b64_e32 v[34:35], 0
	v_mov_b64_e32 v[36:37], 0
	v_mov_b64_e32 v[38:39], 0
	v_mov_b64_e32 v[40:41], 0
	v_mov_b64_e32 v[42:43], 0
	v_mov_b64_e32 v[44:45], 0
	v_mov_b64_e32 v[46:47], 0
	v_mov_b64_e32 v[48:49], 0
	v_mov_b64_e32 v[50:51], 0
	v_mov_b64_e32 v[52:53], 0
	v_mov_b64_e32 v[54:55], 0
	v_mov_b64_e32 v[56:57], 0
	v_mov_b64_e32 v[58:59], 0
	v_mov_b64_e32 v[60:61], 0
	v_mov_b64_e32 v[62:63], 0
	v_mov_b64_e32 v[64:65], 0
	v_mov_b64_e32 v[66:67], 0
	v_mov_b64_e32 v[68:69], 0
	v_mov_b64_e32 v[70:71], 0
	v_mov_b64_e32 v[72:73], 0
	v_mov_b64_e32 v[74:75], 0
	v_mov_b64_e32 v[76:77], 0
	v_mov_b64_e32 v[78:79], 0
	v_mov_b64_e32 v[80:81], 0
	v_mov_b64_e32 v[82:83], 0
	v_mov_b64_e32 v[84:85], 0
	v_mov_b64_e32 v[86:87], 0
	v_mov_b64_e32 v[88:89], 0
	v_mov_b64_e32 v[90:91], 0
	v_mov_b64_e32 v[92:93], 0
	v_mov_b64_e32 v[94:95], 0
	v_mov_b64_e32 v[96:97], 0
	v_mov_b64_e32 v[98:99], 0
	v_mov_b64_e32 v[100:101], 0
	v_mov_b64_e32 v[102:103], 0
	v_mov_b64_e32 v[104:105], 0
	v_mov_b64_e32 v[106:107], 0
	v_mov_b64_e32 v[108:109], 0
	v_mov_b64_e32 v[110:111], 0
	v_mov_b64_e32 v[112:113], 0
	v_mov_b64_e32 v[114:115], 0
	v_mov_b64_e32 v[116:117], 0
	v_mov_b64_e32 v[118:119], 0
	v_mov_b64_e32 v[120:121], 0
	v_mov_b64_e32 v[122:123], 0
	v_mov_b64_e32 v[124:125], 0
	v_mov_b64_e32 v[126:127], 0
	v_mov_b64_e32 v[128:129], 0
	s_add_u32 s48, s46, 0x100
	s_addc_u32 s49, s47, 0
	s_add_i32 s70, 0, 0x10000
	s_cmp_eq_u32 s69, 28
	s_cselect_b32 s55, s17, s49
	s_cselect_b32 s54, s21, s48
	s_cselect_b32 s51, s15, s68
	s_cselect_b32 s50, s66, s67
	s_add_i32 s71, 0, 0x14000
.LBB0_70:
	v_add_u32_e32 v148, s70, v157
	v_add_u32_e32 v168, s71, v157
	ds_read_b128 v[130:133], v148
	ds_read_b128 v[134:137], v148 offset:1024
	ds_read_b128 v[138:141], v148 offset:2048
	ds_read_b128 v[148:151], v148 offset:3072
	ds_read_b128 v[152:155], v168
	ds_read_b128 v[160:163], v168 offset:1024
	ds_read_b128 v[164:167], v168 offset:2048
	ds_read_b128 v[168:171], v168 offset:3072
	s_add_i32 m0, s45, 0xc000
	ds_read_b128 v[172:175], v159
	ds_read_b128 v[176:179], v159 offset:1024
	ds_read_b128 v[180:183], v159 offset:2048
	ds_read_b128 v[200:203], v159 offset:3072
	ds_read_b128 v[204:207], v159 offset:4096
	ds_read_b128 v[208:211], v159 offset:5120
	ds_read_b128 v[212:215], v159 offset:6144
	ds_read_b128 v[216:219], v159 offset:7168
	global_load_lds_dwordx4 v144, s[46:47]
	s_add_i32 m0, s45, 0xe000
	s_nop 0
	global_load_lds_dwordx4 v146, s[46:47]
	s_waitcnt vmcnt(8)
	s_waitcnt lgkmcnt(0)
	s_barrier
	s_waitcnt lgkmcnt(0)
	v_mfma_f32_16x16x32_bf16 v[126:129], v[130:133], v[172:175], v[126:129]
	v_mfma_f32_16x16x32_bf16 v[122:125], v[138:141], v[172:175], v[122:125]
	v_mfma_f32_16x16x32_bf16 v[118:121], v[130:133], v[180:183], v[118:121]
	v_mfma_f32_16x16x32_bf16 v[106:109], v[138:141], v[180:183], v[106:109]
	v_mfma_f32_16x16x32_bf16 v[102:105], v[130:133], v[204:207], v[102:105]
	v_mfma_f32_16x16x32_bf16 v[90:93], v[138:141], v[204:207], v[90:93]
	v_mfma_f32_16x16x32_bf16 v[86:89], v[130:133], v[212:215], v[86:89]
	v_mfma_f32_16x16x32_bf16 v[74:77], v[138:141], v[212:215], v[74:77]
	v_mfma_f32_16x16x32_bf16 v[126:129], v[134:137], v[176:179], v[126:129]
	v_mfma_f32_16x16x32_bf16 v[122:125], v[148:151], v[176:179], v[122:125]
	v_mfma_f32_16x16x32_bf16 v[118:121], v[134:137], v[200:203], v[118:121]
	v_mfma_f32_16x16x32_bf16 v[106:109], v[148:151], v[200:203], v[106:109]
	v_mfma_f32_16x16x32_bf16 v[102:105], v[134:137], v[208:211], v[102:105]
	v_mfma_f32_16x16x32_bf16 v[90:93], v[148:151], v[208:211], v[90:93]
	v_mfma_f32_16x16x32_bf16 v[86:89], v[134:137], v[216:219], v[86:89]
	v_mfma_f32_16x16x32_bf16 v[74:77], v[148:151], v[216:219], v[74:77]
	v_mfma_f32_16x16x32_bf16 v[114:117], v[152:155], v[172:175], v[114:117]
	v_mfma_f32_16x16x32_bf16 v[110:113], v[164:167], v[172:175], v[110:113]
	v_mfma_f32_16x16x32_bf16 v[98:101], v[152:155], v[180:183], v[98:101]
	v_mfma_f32_16x16x32_bf16 v[94:97], v[164:167], v[180:183], v[94:97]
	v_mfma_f32_16x16x32_bf16 v[82:85], v[152:155], v[204:207], v[82:85]
	v_mfma_f32_16x16x32_bf16 v[78:81], v[164:167], v[204:207], v[78:81]
	v_mfma_f32_16x16x32_bf16 v[70:73], v[152:155], v[212:215], v[70:73]
	v_mfma_f32_16x16x32_bf16 v[66:69], v[164:167], v[212:215], v[66:69]
	v_mfma_f32_16x16x32_bf16 v[114:117], v[160:163], v[176:179], v[114:117]
	v_mfma_f32_16x16x32_bf16 v[110:113], v[168:171], v[176:179], v[110:113]
	v_mfma_f32_16x16x32_bf16 v[98:101], v[160:163], v[200:203], v[98:101]
	v_mfma_f32_16x16x32_bf16 v[94:97], v[168:171], v[200:203], v[94:97]
	v_mfma_f32_16x16x32_bf16 v[82:85], v[160:163], v[208:211], v[82:85]
	v_mfma_f32_16x16x32_bf16 v[78:81], v[168:171], v[208:211], v[78:81]
	v_mfma_f32_16x16x32_bf16 v[70:73], v[160:163], v[216:219], v[70:73]
	v_mfma_f32_16x16x32_bf16 v[66:69], v[168:171], v[216:219], v[66:69]
	s_barrier
; #define PG8_STAGE(bufoff, gbase, voff) do { _Pragma("unroll") for (int _i = 0; _i < 2; ++_i) \
;         __builtin_amdgcn_global_load_lds((const unsigned*)((const char*)(gbase) + (voff)[_i]), (LAS unsigned*)(lds + (bufoff) + ldsw + _i * 8192), 16, 0, 0); } while (0)
; #define PG8_LDA(dst, b, h) do { _Pragma("unroll") for (int m = 0; m < 4; ++m) _Pragma("unroll") for (int k = 0; k < 2; ++k) dst[m][k] = *(const LAS bf16x8*)(lds + PG8_SA(b, h) + aoff + m * 2048 + k * 1024); } while (0)
; #define PG8_LDB(dst, b, h) do { _Pragma("unroll") for (int n = 0; n < 2; ++n) _Pragma("unroll") for (int k = 0; k < 2; ++k) dst[n][k] = *(const LAS bf16x8*)(lds + PG8_SB(b, h) + boff + n * 2048 + k * 1024); } while (0)
; #define PG8_MMA(ai, bj, At, Bt) do { __builtin_amdgcn_s_setprio(1); _Pragma("unroll") for (int m = 0; m < 4; ++m) _Pragma("unroll") for (int n = 0; n < 2; ++n) _Pragma("unroll") for (int k = 0; k < 2; ++k) \
;         acc[ai][bj][m][n] = __builtin_amdgcn_mfma_f32_16x16x32_bf16(Bt[n][k], At[m][k], acc[ai][bj][m][n], 0, 0, 0); __builtin_amdgcn_s_setprio(0); } while (0)
; #define PG8_WAIT_V(n) asm volatile("s_waitcnt vmcnt(" #n ")" ::: "memory")
; #define PG8_WAIT_L(n) asm volatile("s_waitcnt lgkmcnt(" #n ")" ::: "memory")
; #define PG8_BAR __builtin_amdgcn_s_barrier()
; #define PG8_SCHED __builtin_amdgcn_sched_barrier(0)
; template <class Epi, class Sched, bool ALIGN_EPI = false, bool SP2 = false>
; __device__ __forceinline__ void gemm_phase(LAS unsigned char* lds, const Gemm g, const Sched& S, const Epi& E, const int tid_) {
;     ...
;             PG8_LDA(At, 0, 1); PG8_STAGE(PG8_SB(0, 0), b2, voffB); PG8_STAGE(PG8_SB(0, 1), b2 + hstep, voffB); PG8_STAGE(PG8_SA(0, 0), a2, voffA);
;             PG8_WAIT_V(8); PG8_WAIT_L(0); PG8_BAR; PG8_MMA(1, 0, At, B0); PG8_MMA(1, 1, At, B1); PG8_BAR; PG8_SCHED;
;             PG8_LDB(B0, 1, 0); PG8_LDB(B1, 1, 1); PG8_SCHED; PG8_LDA(At, 1, 0); PG8_STAGE(PG8_SA(0, 1), a2 + hstep, voffA);
;             PG8_WAIT_V(8); PG8_WAIT_L(0); PG8_BAR; PG8_MMA(0, 0, At, B0); PG8_MMA(0, 1, At, B1); PG8_BAR; PG8_SCHED;
;             PG8_LDA(At, 1, 1); PG8_STAGE(PG8_SB(1, 0), b3, voffB); PG8_STAGE(PG8_SB(1, 1), b3 + hstep, voffB); PG8_STAGE(PG8_SA(1, 0), a3, voffA);
	s_add_i32 s46, s70, s57
	s_mov_b32 m0, s46
	ds_read_b128 v[172:175], v159 offset:16384
	ds_read_b128 v[176:179], v159 offset:17408
	ds_read_b128 v[180:183], v159 offset:18432
	ds_read_b128 v[200:203], v159 offset:19456
	ds_read_b128 v[204:207], v159 offset:20480
	ds_read_b128 v[208:211], v159 offset:21504
	ds_read_b128 v[212:215], v159 offset:22528
	ds_read_b128 v[216:219], v159 offset:23552
	global_load_lds_dwordx4 v0, s[50:51]
	s_add_i32 m0, s46, 0x2000
	s_add_u32 s46, s50, 0x80000
	v_lshl_add_u64 v[192:193], s[50:51], 0, v[142:143]
	s_addc_u32 s47, s51, 0
	s_add_i32 s70, s71, s57
	global_load_lds_dwordx4 v142, s[50:51]
	s_mov_b32 m0, s70
	s_nop 0
	global_load_lds_dwordx4 v0, s[46:47]
	s_add_i32 m0, s70, 0x2000
	s_nop 0
	global_load_lds_dwordx4 v142, s[46:47]
	s_mov_b32 m0, s45
	s_nop 0
	global_load_lds_dwordx4 v0, s[54:55]
	s_mov_b32 m0, s58
	s_nop 0
	global_load_lds_dwordx4 v142, s[54:55]
	s_waitcnt vmcnt(8)
	s_waitcnt lgkmcnt(0)
	s_barrier
	s_waitcnt lgkmcnt(0)
	v_mfma_f32_16x16x32_bf16 v[62:65], v[130:133], v[172:175], v[62:65]
	v_mfma_f32_16x16x32_bf16 v[58:61], v[138:141], v[172:175], v[58:61]
	v_mfma_f32_16x16x32_bf16 v[54:57], v[130:133], v[180:183], v[54:57]
	v_mfma_f32_16x16x32_bf16 v[42:45], v[138:141], v[180:183], v[42:45]
	v_mfma_f32_16x16x32_bf16 v[38:41], v[130:133], v[204:207], v[38:41]
	v_mfma_f32_16x16x32_bf16 v[26:29], v[138:141], v[204:207], v[26:29]
	v_mfma_f32_16x16x32_bf16 v[22:25], v[130:133], v[212:215], v[22:25]
	v_mfma_f32_16x16x32_bf16 v[10:13], v[138:141], v[212:215], v[10:13]
	v_mfma_f32_16x16x32_bf16 v[62:65], v[134:137], v[176:179], v[62:65]
	v_mfma_f32_16x16x32_bf16 v[58:61], v[148:151], v[176:179], v[58:61]
	v_mfma_f32_16x16x32_bf16 v[54:57], v[134:137], v[200:203], v[54:57]
	v_mfma_f32_16x16x32_bf16 v[42:45], v[148:151], v[200:203], v[42:45]
	v_mfma_f32_16x16x32_bf16 v[38:41], v[134:137], v[208:211], v[38:41]
	v_mfma_f32_16x16x32_bf16 v[26:29], v[148:151], v[208:211], v[26:29]
	v_mfma_f32_16x16x32_bf16 v[22:25], v[134:137], v[216:219], v[22:25]
	v_mfma_f32_16x16x32_bf16 v[10:13], v[148:151], v[216:219], v[10:13]
	v_mfma_f32_16x16x32_bf16 v[50:53], v[152:155], v[172:175], v[50:53]
	v_mfma_f32_16x16x32_bf16 v[46:49], v[164:167], v[172:175], v[46:49]
	v_mfma_f32_16x16x32_bf16 v[34:37], v[152:155], v[180:183], v[34:37]
	v_mfma_f32_16x16x32_bf16 v[30:33], v[164:167], v[180:183], v[30:33]
	v_mfma_f32_16x16x32_bf16 v[18:21], v[152:155], v[204:207], v[18:21]
	v_mfma_f32_16x16x32_bf16 v[14:17], v[164:167], v[204:207], v[14:17]
	v_mfma_f32_16x16x32_bf16 v[6:9], v[152:155], v[212:215], v[6:9]
	v_mfma_f32_16x16x32_bf16 v[2:5], v[164:167], v[212:215], v[2:5]
	v_mfma_f32_16x16x32_bf16 v[50:53], v[160:163], v[176:179], v[50:53]
	v_mfma_f32_16x16x32_bf16 v[46:49], v[168:171], v[176:179], v[46:49]
	v_mfma_f32_16x16x32_bf16 v[34:37], v[160:163], v[200:203], v[34:37]
	v_mfma_f32_16x16x32_bf16 v[30:33], v[168:171], v[200:203], v[30:33]
	v_mfma_f32_16x16x32_bf16 v[18:21], v[160:163], v[208:211], v[18:21]
	v_mfma_f32_16x16x32_bf16 v[14:17], v[168:171], v[208:211], v[14:17]
	v_mfma_f32_16x16x32_bf16 v[6:9], v[160:163], v[216:219], v[6:9]
	v_mfma_f32_16x16x32_bf16 v[2:5], v[168:171], v[216:219], v[2:5]
	s_barrier
	s_add_i32 s70, 0, 0x18000
	s_add_i32 s71, 0, 0x1c000
	v_add_u32_e32 v148, s70, v157
	v_add_u32_e32 v168, s71, v157
	ds_read_b128 v[130:133], v148
	ds_read_b128 v[134:137], v148 offset:1024
	ds_read_b128 v[138:141], v148 offset:2048
	ds_read_b128 v[148:151], v148 offset:3072
	ds_read_b128 v[152:155], v168
	ds_read_b128 v[160:163], v168 offset:1024
	ds_read_b128 v[164:167], v168 offset:2048
	ds_read_b128 v[168:171], v168 offset:3072
	s_add_u32 s46, s54, 0x80000
	s_addc_u32 s47, s55, 0
	s_mov_b32 m0, s59
	ds_read_b128 v[172:175], v159 offset:32768
	ds_read_b128 v[176:179], v159 offset:33792
	ds_read_b128 v[180:183], v159 offset:34816
	ds_read_b128 v[200:203], v159 offset:35840
	ds_read_b128 v[204:207], v159 offset:36864
	ds_read_b128 v[208:211], v159 offset:37888
	ds_read_b128 v[212:215], v159 offset:38912
	ds_read_b128 v[216:219], v159 offset:39936
	global_load_lds_dwordx4 v0, s[46:47]
	s_mov_b32 m0, s60
	s_nop 0
	global_load_lds_dwordx4 v142, s[46:47]
	s_waitcnt vmcnt(8)
	s_waitcnt lgkmcnt(0)
	s_barrier
; #define PG8_STAGE(bufoff, gbase, voff) do { _Pragma("unroll") for (int _i = 0; _i < 2; ++_i) \
;         __builtin_amdgcn_global_load_lds((const unsigned*)((const char*)(gbase) + (voff)[_i]), (LAS unsigned*)(lds + (bufoff) + ldsw + _i * 8192), 16, 0, 0); } while (0)
; #define PG8_LDA(dst, b, h) do { _Pragma("unroll") for (int m = 0; m < 4; ++m) _Pragma("unroll") for (int k = 0; k < 2; ++k) dst[m][k] = *(const LAS bf16x8*)(lds + PG8_SA(b, h) + aoff + m * 2048 + k * 1024); } while (0)
; #define PG8_MMA(ai, bj, At, Bt) do { __builtin_amdgcn_s_setprio(1); _Pragma("unroll") for (int m = 0; m < 4; ++m) _Pragma("unroll") for (int n = 0; n < 2; ++n) _Pragma("unroll") for (int k = 0; k < 2; ++k) \
;         acc[ai][bj][m][n] = __builtin_amdgcn_mfma_f32_16x16x32_bf16(Bt[n][k], At[m][k], acc[ai][bj][m][n], 0, 0, 0); __builtin_amdgcn_s_setprio(0); } while (0)
; #define PG8_WAIT_V(n) asm volatile("s_waitcnt vmcnt(" #n ")" ::: "memory")
; #define PG8_WAIT_L(n) asm volatile("s_waitcnt lgkmcnt(" #n ")" ::: "memory")
; #define PG8_BAR __builtin_amdgcn_s_barrier()
; #define PG8_SCHED __builtin_amdgcn_sched_barrier(0)
; template <class Epi, class Sched, bool ALIGN_EPI = false, bool SP2 = false>
; __device__ __forceinline__ void gemm_phase(LAS unsigned char* lds, const Gemm g, const Sched& S, const Epi& E, const int tid_) {
;     ...
;             const char* a2 = last ? nA : cA + (size_t)(t + 2) * kstep; const char* b2 = last ? nB : cB + (size_t)(t + 2) * kstep;
;     ...
;             PG8_WAIT_V(8); PG8_WAIT_L(0); PG8_BAR; PG8_MMA(0, 0, At, B0); PG8_MMA(0, 1, At, B1); PG8_BAR; PG8_SCHED;
;             PG8_LDA(At, 1, 1); PG8_STAGE(PG8_SB(1, 0), b3, voffB); PG8_STAGE(PG8_SB(1, 1), b3 + hstep, voffB); PG8_STAGE(PG8_SA(1, 0), a3, voffA);
;             PG8_WAIT_V(8); PG8_WAIT_L(0); PG8_BAR; PG8_MMA(1, 0, At, B0); PG8_MMA(1, 1, At, B1); PG8_BAR; PG8_SCHED;
	s_waitcnt lgkmcnt(0)
	v_mfma_f32_16x16x32_bf16 v[126:129], v[130:133], v[172:175], v[126:129]
	v_mfma_f32_16x16x32_bf16 v[122:125], v[138:141], v[172:175], v[122:125]
	v_mfma_f32_16x16x32_bf16 v[118:121], v[130:133], v[180:183], v[118:121]
	v_mfma_f32_16x16x32_bf16 v[106:109], v[138:141], v[180:183], v[106:109]
	v_mfma_f32_16x16x32_bf16 v[102:105], v[130:133], v[204:207], v[102:105]
	v_mfma_f32_16x16x32_bf16 v[90:93], v[138:141], v[204:207], v[90:93]
	v_mfma_f32_16x16x32_bf16 v[86:89], v[130:133], v[212:215], v[86:89]
	v_mfma_f32_16x16x32_bf16 v[74:77], v[138:141], v[212:215], v[74:77]
	v_mfma_f32_16x16x32_bf16 v[126:129], v[134:137], v[176:179], v[126:129]
	v_mfma_f32_16x16x32_bf16 v[122:125], v[148:151], v[176:179], v[122:125]
	v_mfma_f32_16x16x32_bf16 v[118:121], v[134:137], v[200:203], v[118:121]
	v_mfma_f32_16x16x32_bf16 v[106:109], v[148:151], v[200:203], v[106:109]
	v_mfma_f32_16x16x32_bf16 v[102:105], v[134:137], v[208:211], v[102:105]
	v_mfma_f32_16x16x32_bf16 v[90:93], v[148:151], v[208:211], v[90:93]
	v_mfma_f32_16x16x32_bf16 v[86:89], v[134:137], v[216:219], v[86:89]
	v_mfma_f32_16x16x32_bf16 v[74:77], v[148:151], v[216:219], v[74:77]
	v_mfma_f32_16x16x32_bf16 v[114:117], v[152:155], v[172:175], v[114:117]
	v_mfma_f32_16x16x32_bf16 v[110:113], v[164:167], v[172:175], v[110:113]
	v_mfma_f32_16x16x32_bf16 v[98:101], v[152:155], v[180:183], v[98:101]
	v_mfma_f32_16x16x32_bf16 v[94:97], v[164:167], v[180:183], v[94:97]
	v_mfma_f32_16x16x32_bf16 v[82:85], v[152:155], v[204:207], v[82:85]
	v_mfma_f32_16x16x32_bf16 v[78:81], v[164:167], v[204:207], v[78:81]
	v_mfma_f32_16x16x32_bf16 v[70:73], v[152:155], v[212:215], v[70:73]
	v_mfma_f32_16x16x32_bf16 v[66:69], v[164:167], v[212:215], v[66:69]
	v_mfma_f32_16x16x32_bf16 v[114:117], v[160:163], v[176:179], v[114:117]
	v_mfma_f32_16x16x32_bf16 v[110:113], v[168:171], v[176:179], v[110:113]
	v_mfma_f32_16x16x32_bf16 v[98:101], v[160:163], v[200:203], v[98:101]
	v_mfma_f32_16x16x32_bf16 v[94:97], v[168:171], v[200:203], v[94:97]
	v_mfma_f32_16x16x32_bf16 v[82:85], v[160:163], v[208:211], v[82:85]
	v_mfma_f32_16x16x32_bf16 v[78:81], v[168:171], v[208:211], v[78:81]
	v_mfma_f32_16x16x32_bf16 v[70:73], v[160:163], v[216:219], v[70:73]
	v_mfma_f32_16x16x32_bf16 v[66:69], v[168:171], v[216:219], v[66:69]
	s_barrier
	s_add_i32 s46, s70, s57
	s_add_i32 m0, s46, 0xffffff80
	ds_read_b128 v[172:175], v159 offset:49152
	ds_read_b128 v[176:179], v159 offset:50176
	ds_read_b128 v[180:183], v159 offset:51200
	ds_read_b128 v[200:203], v159 offset:52224
	ds_read_b128 v[204:207], v159 offset:53248
	ds_read_b128 v[208:211], v159 offset:54272
	ds_read_b128 v[212:215], v159 offset:55296
	ds_read_b128 v[216:219], v159 offset:56320
	global_load_lds_dwordx4 v0, s[50:51] offset:128
	s_add_i32 m0, s46, 0x2000
	s_add_u32 s46, s50, 0x80080
	v_lshl_add_u64 v[184:185], v[192:193], 0, s[96:97]
	s_addc_u32 s47, s51, 0
	s_add_i32 s50, s71, s57
	global_load_lds_dwordx4 v[184:185], off
	s_mov_b32 m0, s50
	s_nop 0
	global_load_lds_dwordx4 v0, s[46:47]
	s_add_i32 m0, s50, 0x2000
	s_nop 0
	global_load_lds_dwordx4 v142, s[46:47]
	s_add_i32 m0, s62, 0xffffff80
	s_nop 0
	global_load_lds_dwordx4 v0, s[54:55] offset:128
	s_add_i32 m0, s63, 0xffffff80
	s_nop 0
	global_load_lds_dwordx4 v142, s[54:55] offset:128
	s_waitcnt vmcnt(8)
	s_waitcnt lgkmcnt(0)
	s_barrier
	s_waitcnt lgkmcnt(0)
	v_mfma_f32_16x16x32_bf16 v[62:65], v[130:133], v[172:175], v[62:65]
	v_mfma_f32_16x16x32_bf16 v[58:61], v[138:141], v[172:175], v[58:61]
	v_mfma_f32_16x16x32_bf16 v[54:57], v[130:133], v[180:183], v[54:57]
	v_mfma_f32_16x16x32_bf16 v[42:45], v[138:141], v[180:183], v[42:45]
	s_add_i32 s69, s69, 2
	s_add_u32 s67, s67, 0x100
	s_addc_u32 s68, s68, 0
	s_mov_b64 s[46:47], s[48:49]
	s_add_u32 s48, s46, 0x100
	s_addc_u32 s49, s47, 0
	s_add_i32 s70, 0, 0x10000
	s_cmp_eq_u32 s69, 28
	s_cselect_b32 s55, s17, s49
	s_cselect_b32 s54, s21, s48
	s_cselect_b32 s51, s15, s68
	s_cselect_b32 s50, s66, s67
	s_add_i32 s71, 0, 0x14000
	v_mfma_f32_16x16x32_bf16 v[38:41], v[130:133], v[204:207], v[38:41]
	v_mfma_f32_16x16x32_bf16 v[26:29], v[138:141], v[204:207], v[26:29]
	v_mfma_f32_16x16x32_bf16 v[22:25], v[130:133], v[212:215], v[22:25]
	v_mfma_f32_16x16x32_bf16 v[10:13], v[138:141], v[212:215], v[10:13]
	v_mfma_f32_16x16x32_bf16 v[62:65], v[134:137], v[176:179], v[62:65]
	v_mfma_f32_16x16x32_bf16 v[58:61], v[148:151], v[176:179], v[58:61]
	v_mfma_f32_16x16x32_bf16 v[54:57], v[134:137], v[200:203], v[54:57]
	v_mfma_f32_16x16x32_bf16 v[42:45], v[148:151], v[200:203], v[42:45]
	v_mfma_f32_16x16x32_bf16 v[38:41], v[134:137], v[208:211], v[38:41]
	v_mfma_f32_16x16x32_bf16 v[26:29], v[148:151], v[208:211], v[26:29]
	v_mfma_f32_16x16x32_bf16 v[22:25], v[134:137], v[216:219], v[22:25]
	v_mfma_f32_16x16x32_bf16 v[10:13], v[148:151], v[216:219], v[10:13]
	v_mfma_f32_16x16x32_bf16 v[50:53], v[152:155], v[172:175], v[50:53]
	v_mfma_f32_16x16x32_bf16 v[46:49], v[164:167], v[172:175], v[46:49]
	v_mfma_f32_16x16x32_bf16 v[34:37], v[152:155], v[180:183], v[34:37]
	v_mfma_f32_16x16x32_bf16 v[30:33], v[164:167], v[180:183], v[30:33]
	v_mfma_f32_16x16x32_bf16 v[18:21], v[152:155], v[204:207], v[18:21]
	v_mfma_f32_16x16x32_bf16 v[14:17], v[164:167], v[204:207], v[14:17]
	v_mfma_f32_16x16x32_bf16 v[6:9], v[152:155], v[212:215], v[6:9]
	v_mfma_f32_16x16x32_bf16 v[2:5], v[164:167], v[212:215], v[2:5]
	v_mfma_f32_16x16x32_bf16 v[50:53], v[160:163], v[176:179], v[50:53]
	v_mfma_f32_16x16x32_bf16 v[46:49], v[168:171], v[176:179], v[46:49]
	v_mfma_f32_16x16x32_bf16 v[34:37], v[160:163], v[200:203], v[34:37]
	v_mfma_f32_16x16x32_bf16 v[30:33], v[168:171], v[200:203], v[30:33]
	v_mfma_f32_16x16x32_bf16 v[18:21], v[160:163], v[208:211], v[18:21]
	v_mfma_f32_16x16x32_bf16 v[14:17], v[168:171], v[208:211], v[14:17]
	v_mfma_f32_16x16x32_bf16 v[6:9], v[160:163], v[216:219], v[6:9]
	v_mfma_f32_16x16x32_bf16 v[2:5], v[168:171], v[216:219], v[2:5]
	s_barrier
	s_cmp_gt_u32 s69, 29
	s_cbranch_scc0 .LBB0_70
	s_andn2_b64 vcc, s[12:13], s[40:41]
	s_cbranch_vccz .LBB0_73
	s_barrier

; #define PG8_STAGE(bufoff, gbase, voff) do { _Pragma("unroll") for (int _i = 0; _i < 2; ++_i) \
;         __builtin_amdgcn_global_load_lds((const unsigned*)((const char*)(gbase) + (voff)[_i]), (LAS unsigned*)(lds + (bufoff) + ldsw + _i * 8192), 16, 0, 0); } while (0)
; #define PG8_LDA(dst, b, h) do { _Pragma("unroll") for (int m = 0; m < 4; ++m) _Pragma("unroll") for (int k = 0; k < 2; ++k) dst[m][k] = *(const LAS bf16x8*)(lds + PG8_SA(b, h) + aoff + m * 2048 + k * 1024); } while (0)
; #define PG8_LDB(dst, b, h) do { _Pragma("unroll") for (int n = 0; n < 2; ++n) _Pragma("unroll") for (int k = 0; k < 2; ++k) dst[n][k] = *(const LAS bf16x8*)(lds + PG8_SB(b, h) + boff + n * 2048 + k * 1024); } while (0)
; #define PG8_WAIT_V(n) asm volatile("s_waitcnt vmcnt(" #n ")" ::: "memory")
; #define PG8_WAIT_L(n) asm volatile("s_waitcnt lgkmcnt(" #n ")" ::: "memory")
; #define PG8_BAR __builtin_amdgcn_s_barrier()
; #define PG8_SCHED __builtin_amdgcn_sched_barrier(0)
; template <class Epi, class Sched, bool ALIGN_EPI = false, bool SP2 = false>
; __device__ __forceinline__ void gemm_phase(LAS unsigned char* lds, const Gemm g, const Sched& S, const Epi& E, const int tid_) {
;     ...
;         const char* nA = has_next ? (const char*)g.A + (size_t)nxt.pm * tstep : cA; const char* nB = has_next ? (const char*)g.Bt + (size_t)nxt.pn * tstep : cB;
;         for (int t = 0; t < nt; t += 2) {
;             const bool last = (t == nt - 2);
;             const char* a1 = cA + (size_t)(t + 1) * kstep;
;             const char* a2 = last ? nA : cA + (size_t)(t + 2) * kstep; const char* b2 = last ? nB : cB + (size_t)(t + 2) * kstep;
;             const char* a3 = a2 + kstep; const char* b3 = b2 + kstep;
;             if (last && has_next) S.a_ready(nxt);
;             if constexpr (SP2) {
;             PG8_LDB(B0, 0, 0); PG8_LDB(B1, 0, 1); PG8_SCHED; PG8_LDA(At, 0, 0); PG8_STAGE(PG8_SA(1, 1), a1 + hstep, voffA);
;             PG8_WAIT_V(8); PG8_WAIT_L(0); PG8_BAR; PG8_MMA(0, 0, At, B0); PG8_MMA(0, 1, At, B1); PG8_BAR; PG8_SCHED;
;     ...
;         for (int a = 0; a < 2; ++a)
; #pragma unroll
;             for (int b = 0; b < 2; ++b)
; #pragma unroll
;                 for (int m = 0; m < 4; ++m)
; #pragma unroll
;                     for (int n = 0; n < 2; ++n) acc[a][b][m][n] = (f32x4){0.f, 0.f, 0.f, 0.f};
;         cur = nxt; cA = nA; cB = nB; ++ui;
.LBB0_95:
	s_ashr_i32 s19, s18, 31
	s_lshl_b64 s[20:21], s[18:19], 19
	s_add_u32 s44, s30, s20
	s_addc_u32 s45, s31, s21
	s_and_b64 s[20:21], s[40:41], exec
	s_cselect_b32 s19, s45, s51
	s_cselect_b32 s20, s44, s50
	s_ashr_i32 s17, s16, 31
	s_lshl_b64 s[46:47], s[16:17], 19
	s_add_u32 s46, s58, s46
	s_addc_u32 s47, s59, s47
	s_and_b64 s[56:57], s[40:41], exec
	s_cselect_b32 s17, s47, s55
	s_cselect_b32 s21, s46, s54
	s_add_u32 s50, s50, 0x40080
	s_addc_u32 s51, s51, 0
	s_add_u32 s69, s54, 0x100
	v_mov_b32_e32 v2, 0
	s_addc_u32 s70, s55, 0
	s_mov_b32 s71, -2
	v_mov_b32_e32 v3, v2
	v_mov_b64_e32 v[4:5], 0
	v_mov_b64_e32 v[6:7], 0
	v_mov_b64_e32 v[8:9], 0
	v_mov_b64_e32 v[10:11], 0
	v_mov_b64_e32 v[12:13], 0
	v_mov_b64_e32 v[14:15], 0
	v_mov_b64_e32 v[16:17], 0
	v_mov_b64_e32 v[18:19], 0
	v_mov_b64_e32 v[20:21], 0
	v_mov_b64_e32 v[22:23], 0
	v_mov_b64_e32 v[24:25], 0
	v_mov_b64_e32 v[26:27], 0
	v_mov_b64_e32 v[28:29], 0
	v_mov_b64_e32 v[30:31], 0
	v_mov_b64_e32 v[32:33], 0
	v_mov_b64_e32 v[34:35], 0
	v_mov_b64_e32 v[36:37], 0
	v_mov_b64_e32 v[38:39], 0
	v_mov_b64_e32 v[40:41], 0
	v_mov_b64_e32 v[42:43], 0
	v_mov_b64_e32 v[44:45], 0
	v_mov_b64_e32 v[46:47], 0
	v_mov_b64_e32 v[48:49], 0
	v_mov_b64_e32 v[50:51], 0
	v_mov_b64_e32 v[52:53], 0
	v_mov_b64_e32 v[54:55], 0
	v_mov_b64_e32 v[56:57], 0
	v_mov_b64_e32 v[58:59], 0
	v_mov_b64_e32 v[60:61], 0
	v_mov_b64_e32 v[62:63], 0
	v_mov_b64_e32 v[64:65], 0
	v_mov_b64_e32 v[66:67], 0
	v_mov_b64_e32 v[68:69], 0
	v_mov_b64_e32 v[70:71], 0
	v_mov_b64_e32 v[72:73], 0
	v_mov_b64_e32 v[74:75], 0
	v_mov_b64_e32 v[76:77], 0
	v_mov_b64_e32 v[78:79], 0
	v_mov_b64_e32 v[80:81], 0
	v_mov_b64_e32 v[82:83], 0
	v_mov_b64_e32 v[84:85], 0
	v_mov_b64_e32 v[86:87], 0
	v_mov_b64_e32 v[88:89], 0
	v_mov_b64_e32 v[90:91], 0
	v_mov_b64_e32 v[92:93], 0
	v_mov_b64_e32 v[94:95], 0
	v_mov_b64_e32 v[96:97], 0
	v_mov_b64_e32 v[98:99], 0
	v_mov_b64_e32 v[100:101], 0
	v_mov_b64_e32 v[102:103], 0
	v_mov_b64_e32 v[104:105], 0
	v_mov_b64_e32 v[106:107], 0
	v_mov_b64_e32 v[108:109], 0
	v_mov_b64_e32 v[110:111], 0
	v_mov_b64_e32 v[112:113], 0
	v_mov_b64_e32 v[114:115], 0
	v_mov_b64_e32 v[116:117], 0
	v_mov_b64_e32 v[118:119], 0
	v_mov_b64_e32 v[120:121], 0
	v_mov_b64_e32 v[122:123], 0
	v_mov_b64_e32 v[124:125], 0
	v_mov_b64_e32 v[126:127], 0
	v_mov_b64_e32 v[128:129], 0
	s_add_u32 s54, s50, 0xfffc0080
	s_addc_u32 s55, s51, -1
	s_add_i32 s72, 0, 0x10000
	s_cmp_eq_u32 s71, 12
	s_cselect_b32 s57, s19, s55
	s_cselect_b32 s56, s20, s54
	s_cselect_b32 s55, s17, s70
	s_cselect_b32 s54, s21, s69
	s_add_i32 s74, 0, 0x14000
.LBB0_96:
	v_add_u32_e32 v142, s72, v177
	v_add_u32_e32 v162, s74, v177
	ds_read_b128 v[130:133], v142
	ds_read_b128 v[134:137], v142 offset:1024
	ds_read_b128 v[138:141], v142 offset:2048
	ds_read_b128 v[142:145], v142 offset:3072
	s_nop 0
	ds_read_b128 v[146:149], v162
	ds_read_b128 v[154:157], v162 offset:1024
	ds_read_b128 v[158:161], v162 offset:2048
	ds_read_b128 v[162:165], v162 offset:3072
	s_add_i32 m0, s49, 0xc000
	ds_read_b128 v[180:183], v179
	ds_read_b128 v[206:209], v179 offset:1024
	ds_read_b128 v[210:213], v179 offset:2048
	ds_read_b128 v[214:217], v179 offset:3072
	ds_read_b128 v[218:221], v179 offset:4096
	ds_read_b128 v[222:225], v179 offset:5120
	ds_read_b128 v[242:245], v179 offset:6144
	ds_read_b128 v[246:249], v179 offset:7168
	global_load_lds_dwordx4 v150, s[50:51]
	s_add_i32 m0, s49, 0xe000
	s_nop 0
	global_load_lds_dwordx4 v152, s[50:51]
	s_waitcnt vmcnt(8)
	s_waitcnt lgkmcnt(0)
	s_barrier
	s_waitcnt lgkmcnt(0)
	v_mfma_f32_16x16x32_bf16 v[126:129], v[130:133], v[180:183], v[126:129]
	v_mfma_f32_16x16x32_bf16 v[122:125], v[138:141], v[180:183], v[122:125]
	v_mfma_f32_16x16x32_bf16 v[118:121], v[130:133], v[210:213], v[118:121]
	v_mfma_f32_16x16x32_bf16 v[114:117], v[138:141], v[210:213], v[114:117]
	v_mfma_f32_16x16x32_bf16 v[98:101], v[130:133], v[218:221], v[98:101]
	v_mfma_f32_16x16x32_bf16 v[90:93], v[138:141], v[218:221], v[90:93]
	v_mfma_f32_16x16x32_bf16 v[82:85], v[130:133], v[242:245], v[82:85]
	v_mfma_f32_16x16x32_bf16 v[74:77], v[138:141], v[242:245], v[74:77]
	v_mfma_f32_16x16x32_bf16 v[126:129], v[134:137], v[206:209], v[126:129]
	v_mfma_f32_16x16x32_bf16 v[122:125], v[142:145], v[206:209], v[122:125]
	v_mfma_f32_16x16x32_bf16 v[118:121], v[134:137], v[214:217], v[118:121]
	v_mfma_f32_16x16x32_bf16 v[114:117], v[142:145], v[214:217], v[114:117]
	v_mfma_f32_16x16x32_bf16 v[98:101], v[134:137], v[222:225], v[98:101]
	v_mfma_f32_16x16x32_bf16 v[90:93], v[142:145], v[222:225], v[90:93]
	v_mfma_f32_16x16x32_bf16 v[82:85], v[134:137], v[246:249], v[82:85]
	v_mfma_f32_16x16x32_bf16 v[74:77], v[142:145], v[246:249], v[74:77]
	v_mfma_f32_16x16x32_bf16 v[110:113], v[146:149], v[180:183], v[110:113]
	v_mfma_f32_16x16x32_bf16 v[106:109], v[158:161], v[180:183], v[106:109]
	v_mfma_f32_16x16x32_bf16 v[102:105], v[146:149], v[210:213], v[102:105]
	v_mfma_f32_16x16x32_bf16 v[94:97], v[158:161], v[210:213], v[94:97]
	v_mfma_f32_16x16x32_bf16 v[86:89], v[146:149], v[218:221], v[86:89]
	v_mfma_f32_16x16x32_bf16 v[78:81], v[158:161], v[218:221], v[78:81]
	v_mfma_f32_16x16x32_bf16 v[70:73], v[146:149], v[242:245], v[70:73]
	v_mfma_f32_16x16x32_bf16 v[66:69], v[158:161], v[242:245], v[66:69]
	v_mfma_f32_16x16x32_bf16 v[110:113], v[154:157], v[206:209], v[110:113]
	v_mfma_f32_16x16x32_bf16 v[106:109], v[162:165], v[206:209], v[106:109]
	v_mfma_f32_16x16x32_bf16 v[102:105], v[154:157], v[214:217], v[102:105]
	v_mfma_f32_16x16x32_bf16 v[94:97], v[162:165], v[214:217], v[94:97]
	v_mfma_f32_16x16x32_bf16 v[86:89], v[154:157], v[222:225], v[86:89]
	v_mfma_f32_16x16x32_bf16 v[78:81], v[162:165], v[222:225], v[78:81]
	v_mfma_f32_16x16x32_bf16 v[70:73], v[154:157], v[246:249], v[70:73]
	v_mfma_f32_16x16x32_bf16 v[66:69], v[162:165], v[246:249], v[66:69]
	s_barrier
; #define PG8_STAGE(bufoff, gbase, voff) do { _Pragma("unroll") for (int _i = 0; _i < 2; ++_i) \
;         __builtin_amdgcn_global_load_lds((const unsigned*)((const char*)(gbase) + (voff)[_i]), (LAS unsigned*)(lds + (bufoff) + ldsw + _i * 8192), 16, 0, 0); } while (0)
; #define PG8_LDA(dst, b, h) do { _Pragma("unroll") for (int m = 0; m < 4; ++m) _Pragma("unroll") for (int k = 0; k < 2; ++k) dst[m][k] = *(const LAS bf16x8*)(lds + PG8_SA(b, h) + aoff + m * 2048 + k * 1024); } while (0)
; #define PG8_LDB(dst, b, h) do { _Pragma("unroll") for (int n = 0; n < 2; ++n) _Pragma("unroll") for (int k = 0; k < 2; ++k) dst[n][k] = *(const LAS bf16x8*)(lds + PG8_SB(b, h) + boff + n * 2048 + k * 1024); } while (0)
; #define PG8_MMA(ai, bj, At, Bt) do { __builtin_amdgcn_s_setprio(1); _Pragma("unroll") for (int m = 0; m < 4; ++m) _Pragma("unroll") for (int n = 0; n < 2; ++n) _Pragma("unroll") for (int k = 0; k < 2; ++k) \
;         acc[ai][bj][m][n] = __builtin_amdgcn_mfma_f32_16x16x32_bf16(Bt[n][k], At[m][k], acc[ai][bj][m][n], 0, 0, 0); __builtin_amdgcn_s_setprio(0); } while (0)
; #define PG8_WAIT_V(n) asm volatile("s_waitcnt vmcnt(" #n ")" ::: "memory")
; #define PG8_WAIT_L(n) asm volatile("s_waitcnt lgkmcnt(" #n ")" ::: "memory")
; #define PG8_BAR __builtin_amdgcn_s_barrier()
; #define PG8_SCHED __builtin_amdgcn_sched_barrier(0)
; template <class Epi, class Sched, bool ALIGN_EPI = false, bool SP2 = false>
; __device__ __forceinline__ void gemm_phase(LAS unsigned char* lds, const Gemm g, const Sched& S, const Epi& E, const int tid_) {
;     ...
;             PG8_LDA(At, 0, 1); PG8_STAGE(PG8_SB(0, 0), b2, voffB); PG8_STAGE(PG8_SB(0, 1), b2 + hstep, voffB); PG8_STAGE(PG8_SA(0, 0), a2, voffA);
;             PG8_WAIT_V(8); PG8_WAIT_L(0); PG8_BAR; PG8_MMA(1, 0, At, B0); PG8_MMA(1, 1, At, B1); PG8_BAR; PG8_SCHED;
;             PG8_LDB(B0, 1, 0); PG8_LDB(B1, 1, 1); PG8_SCHED; PG8_LDA(At, 1, 0); PG8_STAGE(PG8_SA(0, 1), a2 + hstep, voffA);
;             PG8_WAIT_V(8); PG8_WAIT_L(0); PG8_BAR; PG8_MMA(0, 0, At, B0); PG8_MMA(0, 1, At, B1); PG8_BAR; PG8_SCHED;
;             PG8_LDA(At, 1, 1); PG8_STAGE(PG8_SB(1, 0), b3, voffB); PG8_STAGE(PG8_SB(1, 1), b3 + hstep, voffB); PG8_STAGE(PG8_SA(1, 0), a3, voffA);
	s_add_i32 s72, s72, s60
	s_mov_b32 m0, s72
	ds_read_b128 v[180:183], v179 offset:16384
	ds_read_b128 v[206:209], v179 offset:17408
	ds_read_b128 v[210:213], v179 offset:18432
	ds_read_b128 v[214:217], v179 offset:19456
	ds_read_b128 v[218:221], v179 offset:20480
	ds_read_b128 v[222:225], v179 offset:21504
	ds_read_b128 v[242:245], v179 offset:22528
	ds_read_b128 v[246:249], v179 offset:23552
	global_load_lds_dwordx4 v0, s[54:55]
	s_add_i32 m0, s72, 0x2000
	s_add_u32 s72, s54, 0x40000
	v_lshl_add_u64 v[236:237], s[54:55], 0, v[204:205]
	s_addc_u32 s73, s55, 0
	s_add_i32 s74, s74, s60
	global_load_lds_dwordx4 v204, s[54:55]
	s_mov_b32 m0, s74
	v_lshl_add_u64 v[252:253], s[56:57], 0, v[202:203]
	global_load_lds_dwordx4 v0, s[72:73]
	s_add_i32 m0, s74, 0x2000
	s_nop 0
	global_load_lds_dwordx4 v204, s[72:73]
	v_lshl_add_u64 v[250:251], s[56:57], 0, v[200:201]
	s_mov_b32 m0, s49
	s_nop 0
	global_load_lds_dwordx4 v200, s[56:57]
	s_mov_b32 m0, s61
	s_nop 0
	global_load_lds_dwordx4 v202, s[56:57]
	s_waitcnt vmcnt(8)
	s_waitcnt lgkmcnt(0)
	s_barrier
	s_waitcnt lgkmcnt(0)
	v_mfma_f32_16x16x32_bf16 v[62:65], v[130:133], v[180:183], v[62:65]
	v_mfma_f32_16x16x32_bf16 v[58:61], v[138:141], v[180:183], v[58:61]
	v_mfma_f32_16x16x32_bf16 v[50:53], v[130:133], v[210:213], v[50:53]
	v_mfma_f32_16x16x32_bf16 v[42:45], v[138:141], v[210:213], v[42:45]
	v_mfma_f32_16x16x32_bf16 v[34:37], v[130:133], v[218:221], v[34:37]
	v_mfma_f32_16x16x32_bf16 v[26:29], v[138:141], v[218:221], v[26:29]
	v_mfma_f32_16x16x32_bf16 v[18:21], v[130:133], v[242:245], v[18:21]
	v_mfma_f32_16x16x32_bf16 v[10:13], v[138:141], v[242:245], v[10:13]
	v_mfma_f32_16x16x32_bf16 v[62:65], v[134:137], v[206:209], v[62:65]
	v_mfma_f32_16x16x32_bf16 v[58:61], v[142:145], v[206:209], v[58:61]
	v_mfma_f32_16x16x32_bf16 v[50:53], v[134:137], v[214:217], v[50:53]
	v_mfma_f32_16x16x32_bf16 v[42:45], v[142:145], v[214:217], v[42:45]
	v_mfma_f32_16x16x32_bf16 v[34:37], v[134:137], v[222:225], v[34:37]
	v_mfma_f32_16x16x32_bf16 v[26:29], v[142:145], v[222:225], v[26:29]
	v_mfma_f32_16x16x32_bf16 v[18:21], v[134:137], v[246:249], v[18:21]
	v_mfma_f32_16x16x32_bf16 v[10:13], v[142:145], v[246:249], v[10:13]
	v_mfma_f32_16x16x32_bf16 v[54:57], v[146:149], v[180:183], v[54:57]
	v_mfma_f32_16x16x32_bf16 v[46:49], v[158:161], v[180:183], v[46:49]
	v_mfma_f32_16x16x32_bf16 v[38:41], v[146:149], v[210:213], v[38:41]
	v_mfma_f32_16x16x32_bf16 v[30:33], v[158:161], v[210:213], v[30:33]
	v_mfma_f32_16x16x32_bf16 v[22:25], v[146:149], v[218:221], v[22:25]
	v_mfma_f32_16x16x32_bf16 v[14:17], v[158:161], v[218:221], v[14:17]
	v_mfma_f32_16x16x32_bf16 v[6:9], v[146:149], v[242:245], v[6:9]
	v_mfma_f32_16x16x32_bf16 v[2:5], v[158:161], v[242:245], v[2:5]
	v_mfma_f32_16x16x32_bf16 v[54:57], v[154:157], v[206:209], v[54:57]
	v_mfma_f32_16x16x32_bf16 v[46:49], v[162:165], v[206:209], v[46:49]
	v_mfma_f32_16x16x32_bf16 v[38:41], v[154:157], v[214:217], v[38:41]
	v_mfma_f32_16x16x32_bf16 v[30:33], v[162:165], v[214:217], v[30:33]
	v_mfma_f32_16x16x32_bf16 v[22:25], v[154:157], v[222:225], v[22:25]
	v_mfma_f32_16x16x32_bf16 v[14:17], v[162:165], v[222:225], v[14:17]
	v_mfma_f32_16x16x32_bf16 v[6:9], v[154:157], v[246:249], v[6:9]
	v_mfma_f32_16x16x32_bf16 v[2:5], v[162:165], v[246:249], v[2:5]
	s_barrier
	s_add_i32 s72, 0, 0x18000
	s_add_i32 s73, 0, 0x1c000
	v_add_u32_e32 v142, s72, v177
	v_add_u32_e32 v162, s73, v177
	ds_read_b128 v[130:133], v142
	ds_read_b128 v[134:137], v142 offset:1024
	ds_read_b128 v[138:141], v142 offset:2048
	ds_read_b128 v[142:145], v142 offset:3072
	ds_read_b128 v[146:149], v162
	ds_read_b128 v[154:157], v162 offset:1024
	ds_read_b128 v[158:161], v162 offset:2048
	ds_read_b128 v[162:165], v162 offset:3072
	s_add_u32 s56, s56, 0x40000
	s_addc_u32 s57, s57, 0
	s_mov_b32 m0, s62
	ds_read_b128 v[180:183], v179 offset:32768
	ds_read_b128 v[206:209], v179 offset:33792
	ds_read_b128 v[210:213], v179 offset:34816
	ds_read_b128 v[214:217], v179 offset:35840
	ds_read_b128 v[218:221], v179 offset:36864
	ds_read_b128 v[222:225], v179 offset:37888
	ds_read_b128 v[242:245], v179 offset:38912
	ds_read_b128 v[246:249], v179 offset:39936
	global_load_lds_dwordx4 v200, s[56:57]
	s_mov_b32 m0, s63
	s_nop 0
	global_load_lds_dwordx4 v202, s[56:57]
	s_waitcnt vmcnt(8)
	s_waitcnt lgkmcnt(0)
	s_barrier
; #define PG8_STAGE(bufoff, gbase, voff) do { _Pragma("unroll") for (int _i = 0; _i < 2; ++_i) \
;         __builtin_amdgcn_global_load_lds((const unsigned*)((const char*)(gbase) + (voff)[_i]), (LAS unsigned*)(lds + (bufoff) + ldsw + _i * 8192), 16, 0, 0); } while (0)
; #define PG8_LDA(dst, b, h) do { _Pragma("unroll") for (int m = 0; m < 4; ++m) _Pragma("unroll") for (int k = 0; k < 2; ++k) dst[m][k] = *(const LAS bf16x8*)(lds + PG8_SA(b, h) + aoff + m * 2048 + k * 1024); } while (0)
; #define PG8_LDB(dst, b, h) do { _Pragma("unroll") for (int n = 0; n < 2; ++n) _Pragma("unroll") for (int k = 0; k < 2; ++k) dst[n][k] = *(const LAS bf16x8*)(lds + PG8_SB(b, h) + boff + n * 2048 + k * 1024); } while (0)
; template <class Epi, class Sched, bool ALIGN_EPI = false, bool SP2 = false>
; __device__ __forceinline__ void gemm_phase(LAS unsigned char* lds, const Gemm g, const Sched& S, const Epi& E, const int tid_) {
;     ...
;         for (int t = 0; t < nt; t += 2) {
;             const bool last = (t == nt - 2);
;             const char* a1 = cA + (size_t)(t + 1) * kstep;
;             const char* a2 = last ? nA : cA + (size_t)(t + 2) * kstep; const char* b2 = last ? nB : cB + (size_t)(t + 2) * kstep;
;             const char* a3 = a2 + kstep; const char* b3 = b2 + kstep;
;             if (last && has_next) S.a_ready(nxt);
;             if constexpr (SP2) {
;             PG8_LDB(B0, 0, 0); PG8_LDB(B1, 0, 1); PG8_SCHED; PG8_LDA(At, 0, 0); PG8_STAGE(PG8_SA(1, 1), a1 + hstep, voffA);
;             PG8_WAIT_V(8); PG8_WAIT_L(0); PG8_BAR; PG8_MMA(0, 0, At, B0); PG8_MMA(0, 1, At, B1); PG8_BAR; PG8_SCHED;
;             PG8_LDA(At, 0, 1); PG8_STAGE(PG8_SB(0, 0), b2, voffB); PG8_STAGE(PG8_SB(0, 1), b2 + hstep, voffB); PG8_STAGE(PG8_SA(0, 0), a2, voffA);
;             PG8_WAIT_V(8); PG8_WAIT_L(0); PG8_BAR; PG8_MMA(1, 0, At, B0); PG8_MMA(1, 1, At, B1); PG8_BAR; PG8_SCHED;
;             PG8_LDB(B0, 1, 0); PG8_LDB(B1, 1, 1); PG8_SCHED; PG8_LDA(At, 1, 0); PG8_STAGE(PG8_SA(0, 1), a2 + hstep, voffA);
;             PG8_WAIT_V(8); PG8_WAIT_L(0); PG8_BAR; PG8_MMA(0, 0, At, B0); PG8_MMA(0, 1, At, B1); PG8_BAR; PG8_SCHED;
;             PG8_LDA(At, 1, 1); PG8_STAGE(PG8_SB(1, 0), b3, voffB); PG8_STAGE(PG8_SB(1, 1), b3 + hstep, voffB); PG8_STAGE(PG8_SA(1, 0), a3, voffA);
;             PG8_WAIT_V(8); PG8_WAIT_L(0); PG8_BAR; PG8_MMA(1, 0, At, B0); PG8_MMA(1, 1, At, B1); PG8_BAR; PG8_SCHED;
	s_waitcnt lgkmcnt(0)
	v_mfma_f32_16x16x32_bf16 v[126:129], v[130:133], v[180:183], v[126:129]
	v_mfma_f32_16x16x32_bf16 v[122:125], v[138:141], v[180:183], v[122:125]
	v_mfma_f32_16x16x32_bf16 v[118:121], v[130:133], v[210:213], v[118:121]
	v_mfma_f32_16x16x32_bf16 v[114:117], v[138:141], v[210:213], v[114:117]
	v_mfma_f32_16x16x32_bf16 v[98:101], v[130:133], v[218:221], v[98:101]
	v_mfma_f32_16x16x32_bf16 v[90:93], v[138:141], v[218:221], v[90:93]
	v_mfma_f32_16x16x32_bf16 v[82:85], v[130:133], v[242:245], v[82:85]
	v_mfma_f32_16x16x32_bf16 v[74:77], v[138:141], v[242:245], v[74:77]
	v_mfma_f32_16x16x32_bf16 v[126:129], v[134:137], v[206:209], v[126:129]
	v_mfma_f32_16x16x32_bf16 v[122:125], v[142:145], v[206:209], v[122:125]
	v_mfma_f32_16x16x32_bf16 v[118:121], v[134:137], v[214:217], v[118:121]
	v_mfma_f32_16x16x32_bf16 v[114:117], v[142:145], v[214:217], v[114:117]
	v_mfma_f32_16x16x32_bf16 v[98:101], v[134:137], v[222:225], v[98:101]
	v_mfma_f32_16x16x32_bf16 v[90:93], v[142:145], v[222:225], v[90:93]
	v_mfma_f32_16x16x32_bf16 v[82:85], v[134:137], v[246:249], v[82:85]
	v_mfma_f32_16x16x32_bf16 v[74:77], v[142:145], v[246:249], v[74:77]
	v_mfma_f32_16x16x32_bf16 v[110:113], v[146:149], v[180:183], v[110:113]
	v_mfma_f32_16x16x32_bf16 v[106:109], v[158:161], v[180:183], v[106:109]
	v_mfma_f32_16x16x32_bf16 v[102:105], v[146:149], v[210:213], v[102:105]
	v_mfma_f32_16x16x32_bf16 v[94:97], v[158:161], v[210:213], v[94:97]
	v_mfma_f32_16x16x32_bf16 v[86:89], v[146:149], v[218:221], v[86:89]
	v_mfma_f32_16x16x32_bf16 v[78:81], v[158:161], v[218:221], v[78:81]
	v_mfma_f32_16x16x32_bf16 v[70:73], v[146:149], v[242:245], v[70:73]
	v_mfma_f32_16x16x32_bf16 v[66:69], v[158:161], v[242:245], v[66:69]
	v_mfma_f32_16x16x32_bf16 v[110:113], v[154:157], v[206:209], v[110:113]
	v_mfma_f32_16x16x32_bf16 v[106:109], v[162:165], v[206:209], v[106:109]
	v_mfma_f32_16x16x32_bf16 v[102:105], v[154:157], v[214:217], v[102:105]
	v_mfma_f32_16x16x32_bf16 v[94:97], v[162:165], v[214:217], v[94:97]
	v_mfma_f32_16x16x32_bf16 v[86:89], v[154:157], v[222:225], v[86:89]
	v_mfma_f32_16x16x32_bf16 v[78:81], v[162:165], v[222:225], v[78:81]
	v_mfma_f32_16x16x32_bf16 v[70:73], v[154:157], v[246:249], v[70:73]
	v_mfma_f32_16x16x32_bf16 v[66:69], v[162:165], v[246:249], v[66:69]
	s_barrier
	s_add_i32 s56, s72, s60
	s_add_i32 m0, s56, 0xffffff80
	ds_read_b128 v[180:183], v179 offset:49152
	ds_read_b128 v[206:209], v179 offset:50176
	ds_read_b128 v[210:213], v179 offset:51200
	ds_read_b128 v[214:217], v179 offset:52224
	ds_read_b128 v[218:221], v179 offset:53248
	ds_read_b128 v[222:225], v179 offset:54272
	ds_read_b128 v[242:245], v179 offset:55296
	ds_read_b128 v[246:249], v179 offset:56320
	global_load_lds_dwordx4 v0, s[54:55] offset:128
	s_add_i32 m0, s56, 0x2000
	s_add_u32 s54, s54, 0x40080
	v_lshl_add_u64 v[184:185], v[236:237], 0, s[96:97]
	s_addc_u32 s55, s55, 0
	s_add_i32 s56, s73, s60
	global_load_lds_dwordx4 v[184:185], off
	s_mov_b32 m0, s56
	s_nop 0
	global_load_lds_dwordx4 v0, s[54:55]
	s_add_i32 m0, s56, 0x2000
	s_nop 0
	global_load_lds_dwordx4 v204, s[54:55]
	v_lshl_add_u64 v[184:185], v[250:251], 0, s[96:97]
	s_mov_b32 m0, s64
	s_nop 0
	global_load_lds_dwordx4 v[184:185], off
	v_lshl_add_u64 v[184:185], v[252:253], 0, s[96:97]
	s_mov_b32 m0, s65
	s_nop 0
	global_load_lds_dwordx4 v[184:185], off
	s_waitcnt vmcnt(8)
	s_waitcnt lgkmcnt(0)
	s_barrier
	s_waitcnt lgkmcnt(0)
	v_mfma_f32_16x16x32_bf16 v[62:65], v[130:133], v[180:183], v[62:65]
	v_mfma_f32_16x16x32_bf16 v[58:61], v[138:141], v[180:183], v[58:61]
	v_mfma_f32_16x16x32_bf16 v[50:53], v[130:133], v[210:213], v[50:53]
	v_mfma_f32_16x16x32_bf16 v[42:45], v[138:141], v[210:213], v[42:45]
	s_add_i32 s71, s71, 2
	s_add_u32 s50, s50, 0x100
	s_addc_u32 s51, s51, 0
	s_add_u32 s69, s69, 0x100
	s_addc_u32 s70, s70, 0
	s_add_u32 s54, s50, 0xfffc0080
	s_addc_u32 s55, s51, -1
	s_add_i32 s72, 0, 0x10000
	s_cmp_eq_u32 s71, 12
	s_cselect_b32 s57, s19, s55
	s_cselect_b32 s56, s20, s54
	s_cselect_b32 s55, s17, s70
	s_cselect_b32 s54, s21, s69
	s_add_i32 s74, 0, 0x14000
	v_mfma_f32_16x16x32_bf16 v[34:37], v[130:133], v[218:221], v[34:37]
	v_mfma_f32_16x16x32_bf16 v[26:29], v[138:141], v[218:221], v[26:29]
	v_mfma_f32_16x16x32_bf16 v[18:21], v[130:133], v[242:245], v[18:21]
	v_mfma_f32_16x16x32_bf16 v[10:13], v[138:141], v[242:245], v[10:13]
	v_mfma_f32_16x16x32_bf16 v[62:65], v[134:137], v[206:209], v[62:65]
	v_mfma_f32_16x16x32_bf16 v[58:61], v[142:145], v[206:209], v[58:61]
	v_mfma_f32_16x16x32_bf16 v[50:53], v[134:137], v[214:217], v[50:53]
	v_mfma_f32_16x16x32_bf16 v[42:45], v[142:145], v[214:217], v[42:45]
	v_mfma_f32_16x16x32_bf16 v[34:37], v[134:137], v[222:225], v[34:37]
	v_mfma_f32_16x16x32_bf16 v[26:29], v[142:145], v[222:225], v[26:29]
	v_mfma_f32_16x16x32_bf16 v[18:21], v[134:137], v[246:249], v[18:21]
	v_mfma_f32_16x16x32_bf16 v[10:13], v[142:145], v[246:249], v[10:13]
	v_mfma_f32_16x16x32_bf16 v[54:57], v[146:149], v[180:183], v[54:57]
	v_mfma_f32_16x16x32_bf16 v[46:49], v[158:161], v[180:183], v[46:49]
	v_mfma_f32_16x16x32_bf16 v[38:41], v[146:149], v[210:213], v[38:41]
	v_mfma_f32_16x16x32_bf16 v[30:33], v[158:161], v[210:213], v[30:33]
	v_mfma_f32_16x16x32_bf16 v[22:25], v[146:149], v[218:221], v[22:25]
	v_mfma_f32_16x16x32_bf16 v[14:17], v[158:161], v[218:221], v[14:17]
	v_mfma_f32_16x16x32_bf16 v[6:9], v[146:149], v[242:245], v[6:9]
	v_mfma_f32_16x16x32_bf16 v[2:5], v[158:161], v[242:245], v[2:5]
	v_mfma_f32_16x16x32_bf16 v[54:57], v[154:157], v[206:209], v[54:57]
	v_mfma_f32_16x16x32_bf16 v[46:49], v[162:165], v[206:209], v[46:49]
	v_mfma_f32_16x16x32_bf16 v[38:41], v[154:157], v[214:217], v[38:41]
	v_mfma_f32_16x16x32_bf16 v[30:33], v[162:165], v[214:217], v[30:33]
	v_mfma_f32_16x16x32_bf16 v[22:25], v[154:157], v[222:225], v[22:25]
	v_mfma_f32_16x16x32_bf16 v[14:17], v[162:165], v[222:225], v[14:17]
	v_mfma_f32_16x16x32_bf16 v[6:9], v[154:157], v[246:249], v[6:9]
	v_mfma_f32_16x16x32_bf16 v[2:5], v[162:165], v[246:249], v[2:5]
	s_barrier
	s_cmp_gt_u32 s71, 13
	s_cbranch_scc0 .LBB0_96
	s_andn2_b64 vcc, s[14:15], s[40:41]
	s_cbranch_vccz .LBB0_99
	s_barrier

; #define PG8_STAGE(bufoff, gbase, voff) do { _Pragma("unroll") for (int _i = 0; _i < 2; ++_i) \
;         __builtin_amdgcn_global_load_lds((const unsigned*)((const char*)(gbase) + (voff)[_i]), (LAS unsigned*)(lds + (bufoff) + ldsw + _i * 8192), 16, 0, 0); } while (0)
; #define PG8_LDA(dst, b, h) do { _Pragma("unroll") for (int m = 0; m < 4; ++m) _Pragma("unroll") for (int k = 0; k < 2; ++k) dst[m][k] = *(const LAS bf16x8*)(lds + PG8_SA(b, h) + aoff + m * 2048 + k * 1024); } while (0)
; #define PG8_LDB(dst, b, h) do { _Pragma("unroll") for (int n = 0; n < 2; ++n) _Pragma("unroll") for (int k = 0; k < 2; ++k) dst[n][k] = *(const LAS bf16x8*)(lds + PG8_SB(b, h) + boff + n * 2048 + k * 1024); } while (0)
; #define PG8_MMA(ai, bj, At, Bt) do { __builtin_amdgcn_s_setprio(1); _Pragma("unroll") for (int m = 0; m < 4; ++m) _Pragma("unroll") for (int n = 0; n < 2; ++n) _Pragma("unroll") for (int k = 0; k < 2; ++k) \
;         acc[ai][bj][m][n] = __builtin_amdgcn_mfma_f32_16x16x32_bf16(Bt[n][k], At[m][k], acc[ai][bj][m][n], 0, 0, 0); __builtin_amdgcn_s_setprio(0); } while (0)
; #define PG8_WAIT_V(n) asm volatile("s_waitcnt vmcnt(" #n ")" ::: "memory")
; #define PG8_WAIT_L(n) asm volatile("s_waitcnt lgkmcnt(" #n ")" ::: "memory")
; #define PG8_BAR __builtin_amdgcn_s_barrier()
; template <class Epi, class Sched, bool ALIGN_EPI = false, bool SP2 = false>
; __device__ __forceinline__ void gemm_phase(LAS unsigned char* lds, const Gemm g, const Sched& S, const Epi& E, const int tid_) {
;     ...
;         const bool has_next = S.next(ui + 1, nxt);
;         const char* nA = has_next ? (const char*)g.A + (size_t)nxt.pm * tstep : cA; const char* nB = has_next ? (const char*)g.Bt + (size_t)nxt.pn * tstep : cB;
;         for (int t = 0; t < nt; t += 2) {
;             const bool last = (t == nt - 2);
;             const char* a1 = cA + (size_t)(t + 1) * kstep;
;             const char* a2 = last ? nA : cA + (size_t)(t + 2) * kstep; const char* b2 = last ? nB : cB + (size_t)(t + 2) * kstep;
;             const char* a3 = a2 + kstep; const char* b3 = b2 + kstep;
;             if (last && has_next) S.a_ready(nxt);
;             if constexpr (SP2) {
;             PG8_LDB(B0, 0, 0); PG8_LDB(B1, 0, 1); PG8_SCHED; PG8_LDA(At, 0, 0); PG8_STAGE(PG8_SA(1, 1), a1 + hstep, voffA);
;             PG8_WAIT_V(8); PG8_WAIT_L(0); PG8_BAR; PG8_MMA(0, 0, At, B0); PG8_MMA(0, 1, At, B1); PG8_BAR; PG8_SCHED;
.LBB0_119:
	s_ashr_i32 s17, s16, 31
	s_lshl_b64 s[18:19], s[16:17], 19
	s_add_u32 s18, s30, s18
	s_addc_u32 s19, s31, s19
	s_and_b64 s[44:45], s[40:41], exec
	s_cselect_b32 s17, s19, s49
	s_cselect_b32 s21, s18, s48
	s_ashr_i32 s15, s14, 31
	s_lshl_b64 s[44:45], s[14:15], 19
	s_add_u32 s44, s56, s44
	s_addc_u32 s45, s57, s45
	s_and_b64 s[54:55], s[40:41], exec
	s_cselect_b32 s15, s45, s51
	s_cselect_b32 s66, s44, s50
	s_add_u32 s48, s48, 0x40080
	s_addc_u32 s49, s49, 0
	s_add_u32 s67, s50, 0x100
	v_mov_b32_e32 v2, 0
	s_addc_u32 s68, s51, 0
	s_mov_b32 s69, -2
	v_mov_b32_e32 v3, v2
	v_mov_b64_e32 v[4:5], 0
	v_mov_b64_e32 v[6:7], 0
	v_mov_b64_e32 v[8:9], 0
	v_mov_b64_e32 v[10:11], 0
	v_mov_b64_e32 v[12:13], 0
	v_mov_b64_e32 v[14:15], 0
	v_mov_b64_e32 v[16:17], 0
	v_mov_b64_e32 v[18:19], 0
	v_mov_b64_e32 v[20:21], 0
	v_mov_b64_e32 v[22:23], 0
	v_mov_b64_e32 v[24:25], 0
	v_mov_b64_e32 v[26:27], 0
	v_mov_b64_e32 v[28:29], 0
	v_mov_b64_e32 v[30:31], 0
	v_mov_b64_e32 v[32:33], 0
	v_mov_b64_e32 v[34:35], 0
	v_mov_b64_e32 v[36:37], 0
	v_mov_b64_e32 v[38:39], 0
	v_mov_b64_e32 v[40:41], 0
	v_mov_b64_e32 v[42:43], 0
	v_mov_b64_e32 v[44:45], 0
	v_mov_b64_e32 v[46:47], 0
	v_mov_b64_e32 v[48:49], 0
	v_mov_b64_e32 v[50:51], 0
	v_mov_b64_e32 v[52:53], 0
	v_mov_b64_e32 v[54:55], 0
	v_mov_b64_e32 v[56:57], 0
	v_mov_b64_e32 v[58:59], 0
	v_mov_b64_e32 v[60:61], 0
	v_mov_b64_e32 v[62:63], 0
	v_mov_b64_e32 v[64:65], 0
	v_mov_b64_e32 v[66:67], 0
	v_mov_b64_e32 v[68:69], 0
	v_mov_b64_e32 v[70:71], 0
	v_mov_b64_e32 v[72:73], 0
	v_mov_b64_e32 v[74:75], 0
	v_mov_b64_e32 v[76:77], 0
	v_mov_b64_e32 v[78:79], 0
	v_mov_b64_e32 v[80:81], 0
	v_mov_b64_e32 v[82:83], 0
	v_mov_b64_e32 v[84:85], 0
	v_mov_b64_e32 v[86:87], 0
	v_mov_b64_e32 v[88:89], 0
	v_mov_b64_e32 v[90:91], 0
	v_mov_b64_e32 v[92:93], 0
	v_mov_b64_e32 v[94:95], 0
	v_mov_b64_e32 v[96:97], 0
	v_mov_b64_e32 v[98:99], 0
	v_mov_b64_e32 v[100:101], 0
	v_mov_b64_e32 v[102:103], 0
	v_mov_b64_e32 v[104:105], 0
	v_mov_b64_e32 v[106:107], 0
	v_mov_b64_e32 v[108:109], 0
	v_mov_b64_e32 v[110:111], 0
	v_mov_b64_e32 v[112:113], 0
	v_mov_b64_e32 v[114:115], 0
	v_mov_b64_e32 v[116:117], 0
	v_mov_b64_e32 v[118:119], 0
	v_mov_b64_e32 v[120:121], 0
	v_mov_b64_e32 v[122:123], 0
	v_mov_b64_e32 v[124:125], 0
	v_mov_b64_e32 v[126:127], 0
	v_mov_b64_e32 v[128:129], 0
	s_add_u32 s50, s48, 0xfffc0080
	s_addc_u32 s51, s49, -1
	s_add_i32 s70, 0, 0x10000
	s_cmp_eq_u32 s69, 12
	s_cselect_b32 s55, s17, s51
	s_cselect_b32 s54, s21, s50
	s_cselect_b32 s51, s15, s68
	s_cselect_b32 s50, s66, s67
	s_add_i32 s72, 0, 0x14000
.LBB0_120:
	v_add_u32_e32 v142, s70, v199
	v_add_u32_e32 v158, s72, v199
	ds_read_b128 v[130:133], v142
	ds_read_b128 v[134:137], v142 offset:1024
	ds_read_b128 v[138:141], v142 offset:2048
	ds_read_b128 v[142:145], v142 offset:3072
	ds_read_b128 v[146:149], v158
	ds_read_b128 v[150:153], v158 offset:1024
	ds_read_b128 v[154:157], v158 offset:2048
	ds_read_b128 v[158:161], v158 offset:3072
	s_add_i32 m0, s47, 0xc000
	ds_read_b128 v[162:165], v237
	ds_read_b128 v[166:169], v237 offset:1024
	ds_read_b128 v[170:173], v237 offset:2048
	ds_read_b128 v[174:177], v237 offset:3072
	ds_read_b128 v[178:181], v237 offset:4096
	ds_read_b128 v[182:185], v237 offset:5120
	ds_read_b128 v[210:213], v237 offset:6144
	ds_read_b128 v[214:217], v237 offset:7168
	global_load_lds_dwordx4 v206, s[48:49]
	s_add_i32 m0, s47, 0xe000
	s_nop 0
	global_load_lds_dwordx4 v208, s[48:49]
	s_waitcnt vmcnt(8)
	s_waitcnt lgkmcnt(0)
	s_barrier
	s_waitcnt lgkmcnt(0)
	v_mfma_f32_16x16x32_bf16 v[126:129], v[130:133], v[162:165], v[126:129]
	v_mfma_f32_16x16x32_bf16 v[122:125], v[138:141], v[162:165], v[122:125]
	v_mfma_f32_16x16x32_bf16 v[110:113], v[130:133], v[170:173], v[110:113]
	v_mfma_f32_16x16x32_bf16 v[106:109], v[138:141], v[170:173], v[106:109]
	v_mfma_f32_16x16x32_bf16 v[94:97], v[130:133], v[178:181], v[94:97]
	v_mfma_f32_16x16x32_bf16 v[90:93], v[138:141], v[178:181], v[90:93]
	v_mfma_f32_16x16x32_bf16 v[78:81], v[130:133], v[210:213], v[78:81]
	v_mfma_f32_16x16x32_bf16 v[74:77], v[138:141], v[210:213], v[74:77]
	v_mfma_f32_16x16x32_bf16 v[126:129], v[134:137], v[166:169], v[126:129]
	v_mfma_f32_16x16x32_bf16 v[122:125], v[142:145], v[166:169], v[122:125]
	v_mfma_f32_16x16x32_bf16 v[110:113], v[134:137], v[174:177], v[110:113]
	v_mfma_f32_16x16x32_bf16 v[106:109], v[142:145], v[174:177], v[106:109]
	v_mfma_f32_16x16x32_bf16 v[94:97], v[134:137], v[182:185], v[94:97]
	v_mfma_f32_16x16x32_bf16 v[90:93], v[142:145], v[182:185], v[90:93]
	v_mfma_f32_16x16x32_bf16 v[78:81], v[134:137], v[214:217], v[78:81]
	v_mfma_f32_16x16x32_bf16 v[74:77], v[142:145], v[214:217], v[74:77]
	v_mfma_f32_16x16x32_bf16 v[118:121], v[146:149], v[162:165], v[118:121]
	v_mfma_f32_16x16x32_bf16 v[114:117], v[154:157], v[162:165], v[114:117]
	v_mfma_f32_16x16x32_bf16 v[102:105], v[146:149], v[170:173], v[102:105]
	v_mfma_f32_16x16x32_bf16 v[98:101], v[154:157], v[170:173], v[98:101]
	v_mfma_f32_16x16x32_bf16 v[86:89], v[146:149], v[178:181], v[86:89]
	v_mfma_f32_16x16x32_bf16 v[82:85], v[154:157], v[178:181], v[82:85]
	v_mfma_f32_16x16x32_bf16 v[70:73], v[146:149], v[210:213], v[70:73]
	v_mfma_f32_16x16x32_bf16 v[66:69], v[154:157], v[210:213], v[66:69]
	v_mfma_f32_16x16x32_bf16 v[118:121], v[150:153], v[166:169], v[118:121]
	v_mfma_f32_16x16x32_bf16 v[114:117], v[158:161], v[166:169], v[114:117]
	v_mfma_f32_16x16x32_bf16 v[102:105], v[150:153], v[174:177], v[102:105]
	v_mfma_f32_16x16x32_bf16 v[98:101], v[158:161], v[174:177], v[98:101]
	v_mfma_f32_16x16x32_bf16 v[86:89], v[150:153], v[182:185], v[86:89]
	v_mfma_f32_16x16x32_bf16 v[82:85], v[158:161], v[182:185], v[82:85]
	v_mfma_f32_16x16x32_bf16 v[70:73], v[150:153], v[214:217], v[70:73]
	v_mfma_f32_16x16x32_bf16 v[66:69], v[158:161], v[214:217], v[66:69]
	s_barrier
; #define PG8_STAGE(bufoff, gbase, voff) do { _Pragma("unroll") for (int _i = 0; _i < 2; ++_i) \
;         __builtin_amdgcn_global_load_lds((const unsigned*)((const char*)(gbase) + (voff)[_i]), (LAS unsigned*)(lds + (bufoff) + ldsw + _i * 8192), 16, 0, 0); } while (0)
; #define PG8_LDA(dst, b, h) do { _Pragma("unroll") for (int m = 0; m < 4; ++m) _Pragma("unroll") for (int k = 0; k < 2; ++k) dst[m][k] = *(const LAS bf16x8*)(lds + PG8_SA(b, h) + aoff + m * 2048 + k * 1024); } while (0)
; #define PG8_LDB(dst, b, h) do { _Pragma("unroll") for (int n = 0; n < 2; ++n) _Pragma("unroll") for (int k = 0; k < 2; ++k) dst[n][k] = *(const LAS bf16x8*)(lds + PG8_SB(b, h) + boff + n * 2048 + k * 1024); } while (0)
; #define PG8_MMA(ai, bj, At, Bt) do { __builtin_amdgcn_s_setprio(1); _Pragma("unroll") for (int m = 0; m < 4; ++m) _Pragma("unroll") for (int n = 0; n < 2; ++n) _Pragma("unroll") for (int k = 0; k < 2; ++k) \
;         acc[ai][bj][m][n] = __builtin_amdgcn_mfma_f32_16x16x32_bf16(Bt[n][k], At[m][k], acc[ai][bj][m][n], 0, 0, 0); __builtin_amdgcn_s_setprio(0); } while (0)
; #define PG8_WAIT_V(n) asm volatile("s_waitcnt vmcnt(" #n ")" ::: "memory")
; #define PG8_WAIT_L(n) asm volatile("s_waitcnt lgkmcnt(" #n ")" ::: "memory")
; #define PG8_BAR __builtin_amdgcn_s_barrier()
; #define PG8_SCHED __builtin_amdgcn_sched_barrier(0)
; template <class Epi, class Sched, bool ALIGN_EPI = false, bool SP2 = false>
; __device__ __forceinline__ void gemm_phase(LAS unsigned char* lds, const Gemm g, const Sched& S, const Epi& E, const int tid_) {
;     ...
;             PG8_LDA(At, 0, 1); PG8_STAGE(PG8_SB(0, 0), b2, voffB); PG8_STAGE(PG8_SB(0, 1), b2 + hstep, voffB); PG8_STAGE(PG8_SA(0, 0), a2, voffA);
;             PG8_WAIT_V(8); PG8_WAIT_L(0); PG8_BAR; PG8_MMA(1, 0, At, B0); PG8_MMA(1, 1, At, B1); PG8_BAR; PG8_SCHED;
;             PG8_LDB(B0, 1, 0); PG8_LDB(B1, 1, 1); PG8_SCHED; PG8_LDA(At, 1, 0); PG8_STAGE(PG8_SA(0, 1), a2 + hstep, voffA);
;             PG8_WAIT_V(8); PG8_WAIT_L(0); PG8_BAR; PG8_MMA(0, 0, At, B0); PG8_MMA(0, 1, At, B1); PG8_BAR; PG8_SCHED;
	s_add_i32 s70, s70, s58
	s_mov_b32 m0, s70
	ds_read_b128 v[162:165], v237 offset:16384
	ds_read_b128 v[166:169], v237 offset:17408
	ds_read_b128 v[170:173], v237 offset:18432
	ds_read_b128 v[174:177], v237 offset:19456
	ds_read_b128 v[178:181], v237 offset:20480
	ds_read_b128 v[182:185], v237 offset:21504
	ds_read_b128 v[210:213], v237 offset:22528
	ds_read_b128 v[214:217], v237 offset:23552
	global_load_lds_dwordx4 v0, s[50:51]
	s_add_i32 m0, s70, 0x2000
	s_add_u32 s70, s50, 0x40000
	v_lshl_add_u64 v[218:219], s[50:51], 0, v[204:205]
	s_addc_u32 s71, s51, 0
	s_add_i32 s72, s72, s58
	global_load_lds_dwordx4 v204, s[50:51]
	s_mov_b32 m0, s72
	v_lshl_add_u64 v[222:223], s[54:55], 0, v[202:203]
	global_load_lds_dwordx4 v0, s[70:71]
	s_add_i32 m0, s72, 0x2000
	s_nop 0
	global_load_lds_dwordx4 v204, s[70:71]
	v_lshl_add_u64 v[220:221], s[54:55], 0, v[200:201]
	s_mov_b32 m0, s47
	s_nop 0
	global_load_lds_dwordx4 v200, s[54:55]
	s_mov_b32 m0, s59
	s_nop 0
	global_load_lds_dwordx4 v202, s[54:55]
	s_waitcnt vmcnt(8)
	s_waitcnt lgkmcnt(0)
	s_barrier
	s_waitcnt lgkmcnt(0)
	v_mfma_f32_16x16x32_bf16 v[62:65], v[130:133], v[162:165], v[62:65]
	v_mfma_f32_16x16x32_bf16 v[58:61], v[138:141], v[162:165], v[58:61]
	v_mfma_f32_16x16x32_bf16 v[46:49], v[130:133], v[170:173], v[46:49]
	v_mfma_f32_16x16x32_bf16 v[42:45], v[138:141], v[170:173], v[42:45]
	v_mfma_f32_16x16x32_bf16 v[30:33], v[130:133], v[178:181], v[30:33]
	v_mfma_f32_16x16x32_bf16 v[26:29], v[138:141], v[178:181], v[26:29]
	v_mfma_f32_16x16x32_bf16 v[14:17], v[130:133], v[210:213], v[14:17]
	v_mfma_f32_16x16x32_bf16 v[10:13], v[138:141], v[210:213], v[10:13]
	v_mfma_f32_16x16x32_bf16 v[62:65], v[134:137], v[166:169], v[62:65]
	v_mfma_f32_16x16x32_bf16 v[58:61], v[142:145], v[166:169], v[58:61]
	v_mfma_f32_16x16x32_bf16 v[46:49], v[134:137], v[174:177], v[46:49]
	v_mfma_f32_16x16x32_bf16 v[42:45], v[142:145], v[174:177], v[42:45]
	v_mfma_f32_16x16x32_bf16 v[30:33], v[134:137], v[182:185], v[30:33]
	v_mfma_f32_16x16x32_bf16 v[26:29], v[142:145], v[182:185], v[26:29]
	v_mfma_f32_16x16x32_bf16 v[14:17], v[134:137], v[214:217], v[14:17]
	v_mfma_f32_16x16x32_bf16 v[10:13], v[142:145], v[214:217], v[10:13]
	v_mfma_f32_16x16x32_bf16 v[54:57], v[146:149], v[162:165], v[54:57]
	v_mfma_f32_16x16x32_bf16 v[50:53], v[154:157], v[162:165], v[50:53]
	v_mfma_f32_16x16x32_bf16 v[38:41], v[146:149], v[170:173], v[38:41]
	v_mfma_f32_16x16x32_bf16 v[34:37], v[154:157], v[170:173], v[34:37]
	v_mfma_f32_16x16x32_bf16 v[22:25], v[146:149], v[178:181], v[22:25]
	v_mfma_f32_16x16x32_bf16 v[18:21], v[154:157], v[178:181], v[18:21]
	v_mfma_f32_16x16x32_bf16 v[6:9], v[146:149], v[210:213], v[6:9]
	v_mfma_f32_16x16x32_bf16 v[2:5], v[154:157], v[210:213], v[2:5]
	v_mfma_f32_16x16x32_bf16 v[54:57], v[150:153], v[166:169], v[54:57]
	v_mfma_f32_16x16x32_bf16 v[50:53], v[158:161], v[166:169], v[50:53]
	v_mfma_f32_16x16x32_bf16 v[38:41], v[150:153], v[174:177], v[38:41]
	v_mfma_f32_16x16x32_bf16 v[34:37], v[158:161], v[174:177], v[34:37]
	v_mfma_f32_16x16x32_bf16 v[22:25], v[150:153], v[182:185], v[22:25]
	v_mfma_f32_16x16x32_bf16 v[18:21], v[158:161], v[182:185], v[18:21]
	v_mfma_f32_16x16x32_bf16 v[6:9], v[150:153], v[214:217], v[6:9]
	v_mfma_f32_16x16x32_bf16 v[2:5], v[158:161], v[214:217], v[2:5]
	s_barrier
	s_add_i32 s70, 0, 0x18000
	s_add_i32 s71, 0, 0x1c000
	v_add_u32_e32 v142, s70, v199
	v_add_u32_e32 v158, s71, v199
	ds_read_b128 v[130:133], v142
	ds_read_b128 v[134:137], v142 offset:1024
	ds_read_b128 v[138:141], v142 offset:2048
	ds_read_b128 v[142:145], v142 offset:3072
	ds_read_b128 v[146:149], v158
	ds_read_b128 v[150:153], v158 offset:1024
	ds_read_b128 v[154:157], v158 offset:2048
	ds_read_b128 v[158:161], v158 offset:3072
	s_add_u32 s54, s54, 0x40000
	s_addc_u32 s55, s55, 0
	s_mov_b32 m0, s60
	ds_read_b128 v[162:165], v237 offset:32768
	ds_read_b128 v[166:169], v237 offset:33792
	ds_read_b128 v[170:173], v237 offset:34816
	ds_read_b128 v[174:177], v237 offset:35840
	ds_read_b128 v[178:181], v237 offset:36864
	ds_read_b128 v[182:185], v237 offset:37888
	ds_read_b128 v[210:213], v237 offset:38912
	ds_read_b128 v[214:217], v237 offset:39936
	global_load_lds_dwordx4 v200, s[54:55]
	s_mov_b32 m0, s61
	s_nop 0
	global_load_lds_dwordx4 v202, s[54:55]
	s_waitcnt vmcnt(8)
	s_waitcnt lgkmcnt(0)
	s_barrier
; #define PG8_STAGE(bufoff, gbase, voff) do { _Pragma("unroll") for (int _i = 0; _i < 2; ++_i) \
;         __builtin_amdgcn_global_load_lds((const unsigned*)((const char*)(gbase) + (voff)[_i]), (LAS unsigned*)(lds + (bufoff) + ldsw + _i * 8192), 16, 0, 0); } while (0)
; #define PG8_LDA(dst, b, h) do { _Pragma("unroll") for (int m = 0; m < 4; ++m) _Pragma("unroll") for (int k = 0; k < 2; ++k) dst[m][k] = *(const LAS bf16x8*)(lds + PG8_SA(b, h) + aoff + m * 2048 + k * 1024); } while (0)
; #define PG8_MMA(ai, bj, At, Bt) do { __builtin_amdgcn_s_setprio(1); _Pragma("unroll") for (int m = 0; m < 4; ++m) _Pragma("unroll") for (int n = 0; n < 2; ++n) _Pragma("unroll") for (int k = 0; k < 2; ++k) \
;         acc[ai][bj][m][n] = __builtin_amdgcn_mfma_f32_16x16x32_bf16(Bt[n][k], At[m][k], acc[ai][bj][m][n], 0, 0, 0); __builtin_amdgcn_s_setprio(0); } while (0)
; #define PG8_WAIT_V(n) asm volatile("s_waitcnt vmcnt(" #n ")" ::: "memory")
; #define PG8_WAIT_L(n) asm volatile("s_waitcnt lgkmcnt(" #n ")" ::: "memory")
; #define PG8_BAR __builtin_amdgcn_s_barrier()
; #define PG8_SCHED __builtin_amdgcn_sched_barrier(0)
; template <class Epi, class Sched, bool ALIGN_EPI = false, bool SP2 = false>
; __device__ __forceinline__ void gemm_phase(LAS unsigned char* lds, const Gemm g, const Sched& S, const Epi& E, const int tid_) {
;     ...
;         for (int t = 0; t < nt; t += 2) {
;             const bool last = (t == nt - 2);
;             const char* a1 = cA + (size_t)(t + 1) * kstep;
;             const char* a2 = last ? nA : cA + (size_t)(t + 2) * kstep; const char* b2 = last ? nB : cB + (size_t)(t + 2) * kstep;
;             const char* a3 = a2 + kstep; const char* b3 = b2 + kstep;
;     ...
;             PG8_WAIT_V(8); PG8_WAIT_L(0); PG8_BAR; PG8_MMA(0, 0, At, B0); PG8_MMA(0, 1, At, B1); PG8_BAR; PG8_SCHED;
;             PG8_LDA(At, 1, 1); PG8_STAGE(PG8_SB(1, 0), b3, voffB); PG8_STAGE(PG8_SB(1, 1), b3 + hstep, voffB); PG8_STAGE(PG8_SA(1, 0), a3, voffA);
;             PG8_WAIT_V(8); PG8_WAIT_L(0); PG8_BAR; PG8_MMA(1, 0, At, B0); PG8_MMA(1, 1, At, B1); PG8_BAR; PG8_SCHED;
	s_waitcnt lgkmcnt(0)
	v_mfma_f32_16x16x32_bf16 v[126:129], v[130:133], v[162:165], v[126:129]
	v_mfma_f32_16x16x32_bf16 v[122:125], v[138:141], v[162:165], v[122:125]
	v_mfma_f32_16x16x32_bf16 v[110:113], v[130:133], v[170:173], v[110:113]
	v_mfma_f32_16x16x32_bf16 v[106:109], v[138:141], v[170:173], v[106:109]
	v_mfma_f32_16x16x32_bf16 v[94:97], v[130:133], v[178:181], v[94:97]
	v_mfma_f32_16x16x32_bf16 v[90:93], v[138:141], v[178:181], v[90:93]
	v_mfma_f32_16x16x32_bf16 v[78:81], v[130:133], v[210:213], v[78:81]
	v_mfma_f32_16x16x32_bf16 v[74:77], v[138:141], v[210:213], v[74:77]
	v_mfma_f32_16x16x32_bf16 v[126:129], v[134:137], v[166:169], v[126:129]
	v_mfma_f32_16x16x32_bf16 v[122:125], v[142:145], v[166:169], v[122:125]
	v_mfma_f32_16x16x32_bf16 v[110:113], v[134:137], v[174:177], v[110:113]
	v_mfma_f32_16x16x32_bf16 v[106:109], v[142:145], v[174:177], v[106:109]
	v_mfma_f32_16x16x32_bf16 v[94:97], v[134:137], v[182:185], v[94:97]
	v_mfma_f32_16x16x32_bf16 v[90:93], v[142:145], v[182:185], v[90:93]
	v_mfma_f32_16x16x32_bf16 v[78:81], v[134:137], v[214:217], v[78:81]
	v_mfma_f32_16x16x32_bf16 v[74:77], v[142:145], v[214:217], v[74:77]
	v_mfma_f32_16x16x32_bf16 v[118:121], v[146:149], v[162:165], v[118:121]
	v_mfma_f32_16x16x32_bf16 v[114:117], v[154:157], v[162:165], v[114:117]
	v_mfma_f32_16x16x32_bf16 v[102:105], v[146:149], v[170:173], v[102:105]
	v_mfma_f32_16x16x32_bf16 v[98:101], v[154:157], v[170:173], v[98:101]
	v_mfma_f32_16x16x32_bf16 v[86:89], v[146:149], v[178:181], v[86:89]
	v_mfma_f32_16x16x32_bf16 v[82:85], v[154:157], v[178:181], v[82:85]
	v_mfma_f32_16x16x32_bf16 v[70:73], v[146:149], v[210:213], v[70:73]
	v_mfma_f32_16x16x32_bf16 v[66:69], v[154:157], v[210:213], v[66:69]
	v_mfma_f32_16x16x32_bf16 v[118:121], v[150:153], v[166:169], v[118:121]
	v_mfma_f32_16x16x32_bf16 v[114:117], v[158:161], v[166:169], v[114:117]
	v_mfma_f32_16x16x32_bf16 v[102:105], v[150:153], v[174:177], v[102:105]
	v_mfma_f32_16x16x32_bf16 v[98:101], v[158:161], v[174:177], v[98:101]
	v_mfma_f32_16x16x32_bf16 v[86:89], v[150:153], v[182:185], v[86:89]
	v_mfma_f32_16x16x32_bf16 v[82:85], v[158:161], v[182:185], v[82:85]
	v_mfma_f32_16x16x32_bf16 v[70:73], v[150:153], v[214:217], v[70:73]
	v_mfma_f32_16x16x32_bf16 v[66:69], v[158:161], v[214:217], v[66:69]
	s_barrier
	s_add_i32 s54, s70, s58
	s_add_i32 m0, s54, 0xffffff80
	ds_read_b128 v[162:165], v237 offset:49152
	ds_read_b128 v[166:169], v237 offset:50176
	ds_read_b128 v[170:173], v237 offset:51200
	ds_read_b128 v[174:177], v237 offset:52224
	ds_read_b128 v[178:181], v237 offset:53248
	ds_read_b128 v[182:185], v237 offset:54272
	ds_read_b128 v[210:213], v237 offset:55296
	ds_read_b128 v[214:217], v237 offset:56320
	global_load_lds_dwordx4 v0, s[50:51] offset:128
	s_add_i32 m0, s54, 0x2000
	s_add_u32 s50, s50, 0x40080
	v_lshl_add_u64 v[192:193], v[218:219], 0, s[96:97]
	s_addc_u32 s51, s51, 0
	s_add_i32 s54, s71, s58
	global_load_lds_dwordx4 v[192:193], off
	s_mov_b32 m0, s54
	s_nop 0
	global_load_lds_dwordx4 v0, s[50:51]
	s_add_i32 m0, s54, 0x2000
	s_nop 0
	global_load_lds_dwordx4 v204, s[50:51]
	v_lshl_add_u64 v[192:193], v[220:221], 0, s[96:97]
	s_mov_b32 m0, s62
	s_nop 0
	global_load_lds_dwordx4 v[192:193], off
	v_lshl_add_u64 v[192:193], v[222:223], 0, s[96:97]
	s_mov_b32 m0, s63
	s_nop 0
	global_load_lds_dwordx4 v[192:193], off
	s_waitcnt vmcnt(8)
	s_waitcnt lgkmcnt(0)
	s_barrier
	s_waitcnt lgkmcnt(0)
	v_mfma_f32_16x16x32_bf16 v[62:65], v[130:133], v[162:165], v[62:65]
	v_mfma_f32_16x16x32_bf16 v[58:61], v[138:141], v[162:165], v[58:61]
	v_mfma_f32_16x16x32_bf16 v[46:49], v[130:133], v[170:173], v[46:49]
	v_mfma_f32_16x16x32_bf16 v[42:45], v[138:141], v[170:173], v[42:45]
	s_add_i32 s69, s69, 2
	s_add_u32 s48, s48, 0x100
	s_addc_u32 s49, s49, 0
	s_add_u32 s67, s67, 0x100
	s_addc_u32 s68, s68, 0
	s_add_u32 s50, s48, 0xfffc0080
	s_addc_u32 s51, s49, -1
	s_add_i32 s70, 0, 0x10000
	s_cmp_eq_u32 s69, 12
	s_cselect_b32 s55, s17, s51
	s_cselect_b32 s54, s21, s50
	s_cselect_b32 s51, s15, s68
	s_cselect_b32 s50, s66, s67
	s_add_i32 s72, 0, 0x14000
	v_mfma_f32_16x16x32_bf16 v[30:33], v[130:133], v[178:181], v[30:33]
	v_mfma_f32_16x16x32_bf16 v[26:29], v[138:141], v[178:181], v[26:29]
	v_mfma_f32_16x16x32_bf16 v[14:17], v[130:133], v[210:213], v[14:17]
	v_mfma_f32_16x16x32_bf16 v[10:13], v[138:141], v[210:213], v[10:13]
	v_mfma_f32_16x16x32_bf16 v[62:65], v[134:137], v[166:169], v[62:65]
	v_mfma_f32_16x16x32_bf16 v[58:61], v[142:145], v[166:169], v[58:61]
	v_mfma_f32_16x16x32_bf16 v[46:49], v[134:137], v[174:177], v[46:49]
	v_mfma_f32_16x16x32_bf16 v[42:45], v[142:145], v[174:177], v[42:45]
	v_mfma_f32_16x16x32_bf16 v[30:33], v[134:137], v[182:185], v[30:33]
	v_mfma_f32_16x16x32_bf16 v[26:29], v[142:145], v[182:185], v[26:29]
	v_mfma_f32_16x16x32_bf16 v[14:17], v[134:137], v[214:217], v[14:17]
	v_mfma_f32_16x16x32_bf16 v[10:13], v[142:145], v[214:217], v[10:13]
	v_mfma_f32_16x16x32_bf16 v[54:57], v[146:149], v[162:165], v[54:57]
	v_mfma_f32_16x16x32_bf16 v[50:53], v[154:157], v[162:165], v[50:53]
	v_mfma_f32_16x16x32_bf16 v[38:41], v[146:149], v[170:173], v[38:41]
	v_mfma_f32_16x16x32_bf16 v[34:37], v[154:157], v[170:173], v[34:37]
	v_mfma_f32_16x16x32_bf16 v[22:25], v[146:149], v[178:181], v[22:25]
	v_mfma_f32_16x16x32_bf16 v[18:21], v[154:157], v[178:181], v[18:21]
	v_mfma_f32_16x16x32_bf16 v[6:9], v[146:149], v[210:213], v[6:9]
	v_mfma_f32_16x16x32_bf16 v[2:5], v[154:157], v[210:213], v[2:5]
	v_mfma_f32_16x16x32_bf16 v[54:57], v[150:153], v[166:169], v[54:57]
	v_mfma_f32_16x16x32_bf16 v[50:53], v[158:161], v[166:169], v[50:53]
	v_mfma_f32_16x16x32_bf16 v[38:41], v[150:153], v[174:177], v[38:41]
	v_mfma_f32_16x16x32_bf16 v[34:37], v[158:161], v[174:177], v[34:37]
	v_mfma_f32_16x16x32_bf16 v[22:25], v[150:153], v[182:185], v[22:25]
	v_mfma_f32_16x16x32_bf16 v[18:21], v[158:161], v[182:185], v[18:21]
	v_mfma_f32_16x16x32_bf16 v[6:9], v[150:153], v[214:217], v[6:9]
	v_mfma_f32_16x16x32_bf16 v[2:5], v[158:161], v[214:217], v[2:5]
	s_barrier
	s_cmp_gt_u32 s69, 13
	s_cbranch_scc0 .LBB0_120
	s_andn2_b64 vcc, s[12:13], s[40:41]
	s_cbranch_vccz .LBB0_123
	s_barrier

; #define PG8_STAGE(bufoff, gbase, voff) do { _Pragma("unroll") for (int _i = 0; _i < 2; ++_i) \
;         __builtin_amdgcn_global_load_lds((const unsigned*)((const char*)(gbase) + (voff)[_i]), (LAS unsigned*)(lds + (bufoff) + ldsw + _i * 8192), 16, 0, 0); } while (0)
; #define PG8_LDA(dst, b, h) do { _Pragma("unroll") for (int m = 0; m < 4; ++m) _Pragma("unroll") for (int k = 0; k < 2; ++k) dst[m][k] = *(const LAS bf16x8*)(lds + PG8_SA(b, h) + aoff + m * 2048 + k * 1024); } while (0)
; #define PG8_LDB(dst, b, h) do { _Pragma("unroll") for (int n = 0; n < 2; ++n) _Pragma("unroll") for (int k = 0; k < 2; ++k) dst[n][k] = *(const LAS bf16x8*)(lds + PG8_SB(b, h) + boff + n * 2048 + k * 1024); } while (0)
; #define PG8_MMA(ai, bj, At, Bt) do { __builtin_amdgcn_s_setprio(1); _Pragma("unroll") for (int m = 0; m < 4; ++m) _Pragma("unroll") for (int n = 0; n < 2; ++n) _Pragma("unroll") for (int k = 0; k < 2; ++k) \
;         acc[ai][bj][m][n] = __builtin_amdgcn_mfma_f32_16x16x32_bf16(Bt[n][k], At[m][k], acc[ai][bj][m][n], 0, 0, 0); __builtin_amdgcn_s_setprio(0); } while (0)
; #define PG8_WAIT_V(n) asm volatile("s_waitcnt vmcnt(" #n ")" ::: "memory")
; #define PG8_WAIT_L(n) asm volatile("s_waitcnt lgkmcnt(" #n ")" ::: "memory")
; #define PG8_BAR __builtin_amdgcn_s_barrier()
; template <class Epi, class Sched, bool ALIGN_EPI = false, bool SP2 = false>
; __device__ __forceinline__ void gemm_phase(LAS unsigned char* lds, const Gemm g, const Sched& S, const Epi& E, const int tid_) {
;     ...
;         const bool has_next = S.next(ui + 1, nxt);
;         const char* nA = has_next ? (const char*)g.A + (size_t)nxt.pm * tstep : cA; const char* nB = has_next ? (const char*)g.Bt + (size_t)nxt.pn * tstep : cB;
;         for (int t = 0; t < nt; t += 2) {
;             const bool last = (t == nt - 2);
;             const char* a1 = cA + (size_t)(t + 1) * kstep;
;             const char* a2 = last ? nA : cA + (size_t)(t + 2) * kstep; const char* b2 = last ? nB : cB + (size_t)(t + 2) * kstep;
;             const char* a3 = a2 + kstep; const char* b3 = b2 + kstep;
;             if (last && has_next) S.a_ready(nxt);
;             if constexpr (SP2) {
;             PG8_LDB(B0, 0, 0); PG8_LDB(B1, 0, 1); PG8_SCHED; PG8_LDA(At, 0, 0); PG8_STAGE(PG8_SA(1, 1), a1 + hstep, voffA);
;             PG8_WAIT_V(8); PG8_WAIT_L(0); PG8_BAR; PG8_MMA(0, 0, At, B0); PG8_MMA(0, 1, At, B1); PG8_BAR; PG8_SCHED;
.LBB0_358:
	s_ashr_i32 s17, s16, 31
	s_lshl_b64 s[18:19], s[16:17], 22
	s_add_u32 s18, s29, s18
	s_addc_u32 s19, s30, s19
	s_and_b64 s[42:43], s[40:41], exec
	s_cselect_b32 s17, s19, s47
	s_cselect_b32 s21, s18, s46
	s_ashr_i32 s15, s14, 31
	s_lshl_b64 s[42:43], s[14:15], 22
	s_add_u32 s42, s31, s42
	s_addc_u32 s43, s54, s43
	s_and_b64 s[50:51], s[40:41], exec
	s_cselect_b32 s15, s43, s49
	s_cselect_b32 s64, s42, s48
	s_add_u32 s65, s48, 0x100
	v_mov_b32_e32 v2, 0
	s_addc_u32 s66, s49, 0
	s_mov_b32 s67, -2
	v_mov_b32_e32 v3, v2
	v_mov_b64_e32 v[4:5], 0
	v_mov_b64_e32 v[6:7], 0
	v_mov_b64_e32 v[8:9], 0
	v_mov_b64_e32 v[10:11], 0
	v_mov_b64_e32 v[12:13], 0
	v_mov_b64_e32 v[14:15], 0
	v_mov_b64_e32 v[16:17], 0
	v_mov_b64_e32 v[18:19], 0
	v_mov_b64_e32 v[20:21], 0
	v_mov_b64_e32 v[22:23], 0
	v_mov_b64_e32 v[24:25], 0
	v_mov_b64_e32 v[26:27], 0
	v_mov_b64_e32 v[28:29], 0
	v_mov_b64_e32 v[30:31], 0
	v_mov_b64_e32 v[32:33], 0
	v_mov_b64_e32 v[34:35], 0
	v_mov_b64_e32 v[36:37], 0
	v_mov_b64_e32 v[38:39], 0
	v_mov_b64_e32 v[40:41], 0
	v_mov_b64_e32 v[42:43], 0
	v_mov_b64_e32 v[44:45], 0
	v_mov_b64_e32 v[46:47], 0
	v_mov_b64_e32 v[48:49], 0
	v_mov_b64_e32 v[50:51], 0
	v_mov_b64_e32 v[52:53], 0
	v_mov_b64_e32 v[54:55], 0
	v_mov_b64_e32 v[56:57], 0
	v_mov_b64_e32 v[58:59], 0
	v_mov_b64_e32 v[60:61], 0
	v_mov_b64_e32 v[62:63], 0
	v_mov_b64_e32 v[64:65], 0
	v_mov_b64_e32 v[66:67], 0
	v_mov_b64_e32 v[68:69], 0
	v_mov_b64_e32 v[70:71], 0
	v_mov_b64_e32 v[72:73], 0
	v_mov_b64_e32 v[74:75], 0
	v_mov_b64_e32 v[76:77], 0
	v_mov_b64_e32 v[78:79], 0
	v_mov_b64_e32 v[80:81], 0
	v_mov_b64_e32 v[82:83], 0
	v_mov_b64_e32 v[84:85], 0
	v_mov_b64_e32 v[86:87], 0
	v_mov_b64_e32 v[88:89], 0
	v_mov_b64_e32 v[90:91], 0
	v_mov_b64_e32 v[92:93], 0
	v_mov_b64_e32 v[94:95], 0
	v_mov_b64_e32 v[96:97], 0
	v_mov_b64_e32 v[98:99], 0
	v_mov_b64_e32 v[100:101], 0
	v_mov_b64_e32 v[102:103], 0
	v_mov_b64_e32 v[104:105], 0
	v_mov_b64_e32 v[106:107], 0
	v_mov_b64_e32 v[108:109], 0
	v_mov_b64_e32 v[110:111], 0
	v_mov_b64_e32 v[112:113], 0
	v_mov_b64_e32 v[114:115], 0
	v_mov_b64_e32 v[116:117], 0
	v_mov_b64_e32 v[118:119], 0
	v_mov_b64_e32 v[120:121], 0
	v_mov_b64_e32 v[122:123], 0
	v_mov_b64_e32 v[124:125], 0
	v_mov_b64_e32 v[126:127], 0
	v_mov_b64_e32 v[128:129], 0
	s_add_u32 s48, s46, 0x100
	s_addc_u32 s49, s47, 0
	s_add_i32 s68, 0, 0x10000
	s_cmpk_eq_i32 s67, 0x7c
	s_cselect_b32 s53, s17, s49
	s_cselect_b32 s52, s21, s48
	s_cselect_b32 s51, s15, s66
	s_cselect_b32 s50, s64, s65
	s_add_i32 s69, 0, 0x14000
.LBB0_359:
	v_add_u32_e32 v148, s68, v157
	v_add_u32_e32 v168, s69, v157
	ds_read_b128 v[130:133], v148
	ds_read_b128 v[134:137], v148 offset:1024
	ds_read_b128 v[138:141], v148 offset:2048
	ds_read_b128 v[148:151], v148 offset:3072
	ds_read_b128 v[152:155], v168
	ds_read_b128 v[160:163], v168 offset:1024
	ds_read_b128 v[164:167], v168 offset:2048
	ds_read_b128 v[168:171], v168 offset:3072
	s_add_i32 m0, s45, 0xc000
	ds_read_b128 v[172:175], v159
	ds_read_b128 v[176:179], v159 offset:1024
	ds_read_b128 v[180:183], v159 offset:2048
	ds_read_b128 v[200:203], v159 offset:3072
	ds_read_b128 v[204:207], v159 offset:4096
	ds_read_b128 v[208:211], v159 offset:5120
	ds_read_b128 v[212:215], v159 offset:6144
	ds_read_b128 v[216:219], v159 offset:7168
	global_load_lds_dwordx4 v144, s[46:47]
	s_add_i32 m0, s45, 0xe000
	s_nop 0
	global_load_lds_dwordx4 v146, s[46:47]
	s_waitcnt vmcnt(8)
	s_waitcnt lgkmcnt(0)
	s_barrier
	s_waitcnt lgkmcnt(0)
	v_mfma_f32_16x16x32_bf16 v[126:129], v[130:133], v[172:175], v[126:129]
	v_mfma_f32_16x16x32_bf16 v[122:125], v[138:141], v[172:175], v[122:125]
	v_mfma_f32_16x16x32_bf16 v[118:121], v[130:133], v[180:183], v[118:121]
	v_mfma_f32_16x16x32_bf16 v[106:109], v[138:141], v[180:183], v[106:109]
	v_mfma_f32_16x16x32_bf16 v[102:105], v[130:133], v[204:207], v[102:105]
	v_mfma_f32_16x16x32_bf16 v[90:93], v[138:141], v[204:207], v[90:93]
	v_mfma_f32_16x16x32_bf16 v[86:89], v[130:133], v[212:215], v[86:89]
	v_mfma_f32_16x16x32_bf16 v[74:77], v[138:141], v[212:215], v[74:77]
	v_mfma_f32_16x16x32_bf16 v[126:129], v[134:137], v[176:179], v[126:129]
	v_mfma_f32_16x16x32_bf16 v[122:125], v[148:151], v[176:179], v[122:125]
	v_mfma_f32_16x16x32_bf16 v[118:121], v[134:137], v[200:203], v[118:121]
	v_mfma_f32_16x16x32_bf16 v[106:109], v[148:151], v[200:203], v[106:109]
	v_mfma_f32_16x16x32_bf16 v[102:105], v[134:137], v[208:211], v[102:105]
	v_mfma_f32_16x16x32_bf16 v[90:93], v[148:151], v[208:211], v[90:93]
	v_mfma_f32_16x16x32_bf16 v[86:89], v[134:137], v[216:219], v[86:89]
	v_mfma_f32_16x16x32_bf16 v[74:77], v[148:151], v[216:219], v[74:77]
	v_mfma_f32_16x16x32_bf16 v[114:117], v[152:155], v[172:175], v[114:117]
	v_mfma_f32_16x16x32_bf16 v[110:113], v[164:167], v[172:175], v[110:113]
	v_mfma_f32_16x16x32_bf16 v[98:101], v[152:155], v[180:183], v[98:101]
	v_mfma_f32_16x16x32_bf16 v[94:97], v[164:167], v[180:183], v[94:97]
	v_mfma_f32_16x16x32_bf16 v[82:85], v[152:155], v[204:207], v[82:85]
	v_mfma_f32_16x16x32_bf16 v[78:81], v[164:167], v[204:207], v[78:81]
	v_mfma_f32_16x16x32_bf16 v[70:73], v[152:155], v[212:215], v[70:73]
	v_mfma_f32_16x16x32_bf16 v[66:69], v[164:167], v[212:215], v[66:69]
	v_mfma_f32_16x16x32_bf16 v[114:117], v[160:163], v[176:179], v[114:117]
	v_mfma_f32_16x16x32_bf16 v[110:113], v[168:171], v[176:179], v[110:113]
	v_mfma_f32_16x16x32_bf16 v[98:101], v[160:163], v[200:203], v[98:101]
	v_mfma_f32_16x16x32_bf16 v[94:97], v[168:171], v[200:203], v[94:97]
	v_mfma_f32_16x16x32_bf16 v[82:85], v[160:163], v[208:211], v[82:85]
	v_mfma_f32_16x16x32_bf16 v[78:81], v[168:171], v[208:211], v[78:81]
	v_mfma_f32_16x16x32_bf16 v[70:73], v[160:163], v[216:219], v[70:73]
	v_mfma_f32_16x16x32_bf16 v[66:69], v[168:171], v[216:219], v[66:69]
	s_barrier
; #define PG8_STAGE(bufoff, gbase, voff) do { _Pragma("unroll") for (int _i = 0; _i < 2; ++_i) \
;         __builtin_amdgcn_global_load_lds((const unsigned*)((const char*)(gbase) + (voff)[_i]), (LAS unsigned*)(lds + (bufoff) + ldsw + _i * 8192), 16, 0, 0); } while (0)
; #define PG8_LDA(dst, b, h) do { _Pragma("unroll") for (int m = 0; m < 4; ++m) _Pragma("unroll") for (int k = 0; k < 2; ++k) dst[m][k] = *(const LAS bf16x8*)(lds + PG8_SA(b, h) + aoff + m * 2048 + k * 1024); } while (0)
; #define PG8_LDB(dst, b, h) do { _Pragma("unroll") for (int n = 0; n < 2; ++n) _Pragma("unroll") for (int k = 0; k < 2; ++k) dst[n][k] = *(const LAS bf16x8*)(lds + PG8_SB(b, h) + boff + n * 2048 + k * 1024); } while (0)
; #define PG8_MMA(ai, bj, At, Bt) do { __builtin_amdgcn_s_setprio(1); _Pragma("unroll") for (int m = 0; m < 4; ++m) _Pragma("unroll") for (int n = 0; n < 2; ++n) _Pragma("unroll") for (int k = 0; k < 2; ++k) \
;         acc[ai][bj][m][n] = __builtin_amdgcn_mfma_f32_16x16x32_bf16(Bt[n][k], At[m][k], acc[ai][bj][m][n], 0, 0, 0); __builtin_amdgcn_s_setprio(0); } while (0)
; #define PG8_WAIT_V(n) asm volatile("s_waitcnt vmcnt(" #n ")" ::: "memory")
; #define PG8_WAIT_L(n) asm volatile("s_waitcnt lgkmcnt(" #n ")" ::: "memory")
; #define PG8_BAR __builtin_amdgcn_s_barrier()
; #define PG8_SCHED __builtin_amdgcn_sched_barrier(0)
; template <class Epi, class Sched, bool ALIGN_EPI = false, bool SP2 = false>
; __device__ __forceinline__ void gemm_phase(LAS unsigned char* lds, const Gemm g, const Sched& S, const Epi& E, const int tid_) {
;     ...
;             PG8_LDA(At, 0, 1); PG8_STAGE(PG8_SB(0, 0), b2, voffB); PG8_STAGE(PG8_SB(0, 1), b2 + hstep, voffB); PG8_STAGE(PG8_SA(0, 0), a2, voffA);
;             PG8_WAIT_V(8); PG8_WAIT_L(0); PG8_BAR; PG8_MMA(1, 0, At, B0); PG8_MMA(1, 1, At, B1); PG8_BAR; PG8_SCHED;
;             PG8_LDB(B0, 1, 0); PG8_LDB(B1, 1, 1); PG8_SCHED; PG8_LDA(At, 1, 0); PG8_STAGE(PG8_SA(0, 1), a2 + hstep, voffA);
;             PG8_WAIT_V(8); PG8_WAIT_L(0); PG8_BAR; PG8_MMA(0, 0, At, B0); PG8_MMA(0, 1, At, B1); PG8_BAR; PG8_SCHED;
	s_add_i32 s46, s68, s55
	s_mov_b32 m0, s46
	ds_read_b128 v[172:175], v159 offset:16384
	ds_read_b128 v[176:179], v159 offset:17408
	ds_read_b128 v[180:183], v159 offset:18432
	ds_read_b128 v[200:203], v159 offset:19456
	ds_read_b128 v[204:207], v159 offset:20480
	ds_read_b128 v[208:211], v159 offset:21504
	ds_read_b128 v[212:215], v159 offset:22528
	ds_read_b128 v[216:219], v159 offset:23552
	global_load_lds_dwordx4 v0, s[50:51]
	s_add_i32 m0, s46, 0x2000
	s_add_u32 s46, s50, 0x200000
	v_lshl_add_u64 v[192:193], s[50:51], 0, v[142:143]
	s_addc_u32 s47, s51, 0
	s_add_i32 s68, s69, s55
	global_load_lds_dwordx4 v142, s[50:51]
	s_mov_b32 m0, s68
	s_nop 0
	global_load_lds_dwordx4 v0, s[46:47]
	s_add_i32 m0, s68, 0x2000
	s_nop 0
	global_load_lds_dwordx4 v142, s[46:47]
	s_mov_b32 m0, s45
	s_nop 0
	global_load_lds_dwordx4 v0, s[52:53]
	s_mov_b32 m0, s56
	s_nop 0
	global_load_lds_dwordx4 v142, s[52:53]
	s_waitcnt vmcnt(8)
	s_waitcnt lgkmcnt(0)
	s_barrier
	s_waitcnt lgkmcnt(0)
	v_mfma_f32_16x16x32_bf16 v[62:65], v[130:133], v[172:175], v[62:65]
	v_mfma_f32_16x16x32_bf16 v[58:61], v[138:141], v[172:175], v[58:61]
	v_mfma_f32_16x16x32_bf16 v[54:57], v[130:133], v[180:183], v[54:57]
	v_mfma_f32_16x16x32_bf16 v[42:45], v[138:141], v[180:183], v[42:45]
	v_mfma_f32_16x16x32_bf16 v[38:41], v[130:133], v[204:207], v[38:41]
	v_mfma_f32_16x16x32_bf16 v[26:29], v[138:141], v[204:207], v[26:29]
	v_mfma_f32_16x16x32_bf16 v[22:25], v[130:133], v[212:215], v[22:25]
	v_mfma_f32_16x16x32_bf16 v[10:13], v[138:141], v[212:215], v[10:13]
	v_mfma_f32_16x16x32_bf16 v[62:65], v[134:137], v[176:179], v[62:65]
	v_mfma_f32_16x16x32_bf16 v[58:61], v[148:151], v[176:179], v[58:61]
	v_mfma_f32_16x16x32_bf16 v[54:57], v[134:137], v[200:203], v[54:57]
	v_mfma_f32_16x16x32_bf16 v[42:45], v[148:151], v[200:203], v[42:45]
	v_mfma_f32_16x16x32_bf16 v[38:41], v[134:137], v[208:211], v[38:41]
	v_mfma_f32_16x16x32_bf16 v[26:29], v[148:151], v[208:211], v[26:29]
	v_mfma_f32_16x16x32_bf16 v[22:25], v[134:137], v[216:219], v[22:25]
	v_mfma_f32_16x16x32_bf16 v[10:13], v[148:151], v[216:219], v[10:13]
	v_mfma_f32_16x16x32_bf16 v[50:53], v[152:155], v[172:175], v[50:53]
	v_mfma_f32_16x16x32_bf16 v[46:49], v[164:167], v[172:175], v[46:49]
	v_mfma_f32_16x16x32_bf16 v[34:37], v[152:155], v[180:183], v[34:37]
	v_mfma_f32_16x16x32_bf16 v[30:33], v[164:167], v[180:183], v[30:33]
	v_mfma_f32_16x16x32_bf16 v[18:21], v[152:155], v[204:207], v[18:21]
	v_mfma_f32_16x16x32_bf16 v[14:17], v[164:167], v[204:207], v[14:17]
	v_mfma_f32_16x16x32_bf16 v[6:9], v[152:155], v[212:215], v[6:9]
	v_mfma_f32_16x16x32_bf16 v[2:5], v[164:167], v[212:215], v[2:5]
	v_mfma_f32_16x16x32_bf16 v[50:53], v[160:163], v[176:179], v[50:53]
	v_mfma_f32_16x16x32_bf16 v[46:49], v[168:171], v[176:179], v[46:49]
	v_mfma_f32_16x16x32_bf16 v[34:37], v[160:163], v[200:203], v[34:37]
	v_mfma_f32_16x16x32_bf16 v[30:33], v[168:171], v[200:203], v[30:33]
	v_mfma_f32_16x16x32_bf16 v[18:21], v[160:163], v[208:211], v[18:21]
	v_mfma_f32_16x16x32_bf16 v[14:17], v[168:171], v[208:211], v[14:17]
	v_mfma_f32_16x16x32_bf16 v[6:9], v[160:163], v[216:219], v[6:9]
	v_mfma_f32_16x16x32_bf16 v[2:5], v[168:171], v[216:219], v[2:5]
	s_barrier
	s_add_i32 s68, 0, 0x18000
	s_add_i32 s69, 0, 0x1c000
	v_add_u32_e32 v148, s68, v157
	v_add_u32_e32 v168, s69, v157
	ds_read_b128 v[130:133], v148
	ds_read_b128 v[134:137], v148 offset:1024
	ds_read_b128 v[138:141], v148 offset:2048
	ds_read_b128 v[148:151], v148 offset:3072
	ds_read_b128 v[152:155], v168
	ds_read_b128 v[160:163], v168 offset:1024
	ds_read_b128 v[164:167], v168 offset:2048
	ds_read_b128 v[168:171], v168 offset:3072
	s_add_u32 s46, s52, 0x200000
	s_addc_u32 s47, s53, 0
	s_mov_b32 m0, s57
	ds_read_b128 v[172:175], v159 offset:32768
	ds_read_b128 v[176:179], v159 offset:33792
	ds_read_b128 v[180:183], v159 offset:34816
	ds_read_b128 v[200:203], v159 offset:35840
	ds_read_b128 v[204:207], v159 offset:36864
	ds_read_b128 v[208:211], v159 offset:37888
	ds_read_b128 v[212:215], v159 offset:38912
	ds_read_b128 v[216:219], v159 offset:39936
	global_load_lds_dwordx4 v0, s[46:47]
	s_mov_b32 m0, s58
	s_nop 0
	global_load_lds_dwordx4 v142, s[46:47]
	s_waitcnt vmcnt(8)
	s_waitcnt lgkmcnt(0)
	s_barrier
; #define PG8_STAGE(bufoff, gbase, voff) do { _Pragma("unroll") for (int _i = 0; _i < 2; ++_i) \
;         __builtin_amdgcn_global_load_lds((const unsigned*)((const char*)(gbase) + (voff)[_i]), (LAS unsigned*)(lds + (bufoff) + ldsw + _i * 8192), 16, 0, 0); } while (0)
; #define PG8_LDA(dst, b, h) do { _Pragma("unroll") for (int m = 0; m < 4; ++m) _Pragma("unroll") for (int k = 0; k < 2; ++k) dst[m][k] = *(const LAS bf16x8*)(lds + PG8_SA(b, h) + aoff + m * 2048 + k * 1024); } while (0)
; #define PG8_MMA(ai, bj, At, Bt) do { __builtin_amdgcn_s_setprio(1); _Pragma("unroll") for (int m = 0; m < 4; ++m) _Pragma("unroll") for (int n = 0; n < 2; ++n) _Pragma("unroll") for (int k = 0; k < 2; ++k) \
;         acc[ai][bj][m][n] = __builtin_amdgcn_mfma_f32_16x16x32_bf16(Bt[n][k], At[m][k], acc[ai][bj][m][n], 0, 0, 0); __builtin_amdgcn_s_setprio(0); } while (0)
; #define PG8_WAIT_V(n) asm volatile("s_waitcnt vmcnt(" #n ")" ::: "memory")
; #define PG8_WAIT_L(n) asm volatile("s_waitcnt lgkmcnt(" #n ")" ::: "memory")
; #define PG8_BAR __builtin_amdgcn_s_barrier()
; #define PG8_SCHED __builtin_amdgcn_sched_barrier(0)
; template <class Epi, class Sched, bool ALIGN_EPI = false, bool SP2 = false>
; __device__ __forceinline__ void gemm_phase(LAS unsigned char* lds, const Gemm g, const Sched& S, const Epi& E, const int tid_) {
;     ...
;         for (int t = 0; t < nt; t += 2) {
;             const bool last = (t == nt - 2);
;             const char* a1 = cA + (size_t)(t + 1) * kstep;
;             const char* a2 = last ? nA : cA + (size_t)(t + 2) * kstep; const char* b2 = last ? nB : cB + (size_t)(t + 2) * kstep;
;             const char* a3 = a2 + kstep; const char* b3 = b2 + kstep;
;     ...
;             PG8_WAIT_V(8); PG8_WAIT_L(0); PG8_BAR; PG8_MMA(0, 0, At, B0); PG8_MMA(0, 1, At, B1); PG8_BAR; PG8_SCHED;
;             PG8_LDA(At, 1, 1); PG8_STAGE(PG8_SB(1, 0), b3, voffB); PG8_STAGE(PG8_SB(1, 1), b3 + hstep, voffB); PG8_STAGE(PG8_SA(1, 0), a3, voffA);
;             PG8_WAIT_V(8); PG8_WAIT_L(0); PG8_BAR; PG8_MMA(1, 0, At, B0); PG8_MMA(1, 1, At, B1); PG8_BAR; PG8_SCHED;
	s_waitcnt lgkmcnt(0)
	v_mfma_f32_16x16x32_bf16 v[126:129], v[130:133], v[172:175], v[126:129]
	v_mfma_f32_16x16x32_bf16 v[122:125], v[138:141], v[172:175], v[122:125]
	v_mfma_f32_16x16x32_bf16 v[118:121], v[130:133], v[180:183], v[118:121]
	v_mfma_f32_16x16x32_bf16 v[106:109], v[138:141], v[180:183], v[106:109]
	v_mfma_f32_16x16x32_bf16 v[102:105], v[130:133], v[204:207], v[102:105]
	v_mfma_f32_16x16x32_bf16 v[90:93], v[138:141], v[204:207], v[90:93]
	v_mfma_f32_16x16x32_bf16 v[86:89], v[130:133], v[212:215], v[86:89]
	v_mfma_f32_16x16x32_bf16 v[74:77], v[138:141], v[212:215], v[74:77]
	v_mfma_f32_16x16x32_bf16 v[126:129], v[134:137], v[176:179], v[126:129]
	v_mfma_f32_16x16x32_bf16 v[122:125], v[148:151], v[176:179], v[122:125]
	v_mfma_f32_16x16x32_bf16 v[118:121], v[134:137], v[200:203], v[118:121]
	v_mfma_f32_16x16x32_bf16 v[106:109], v[148:151], v[200:203], v[106:109]
	v_mfma_f32_16x16x32_bf16 v[102:105], v[134:137], v[208:211], v[102:105]
	v_mfma_f32_16x16x32_bf16 v[90:93], v[148:151], v[208:211], v[90:93]
	v_mfma_f32_16x16x32_bf16 v[86:89], v[134:137], v[216:219], v[86:89]
	v_mfma_f32_16x16x32_bf16 v[74:77], v[148:151], v[216:219], v[74:77]
	v_mfma_f32_16x16x32_bf16 v[114:117], v[152:155], v[172:175], v[114:117]
	v_mfma_f32_16x16x32_bf16 v[110:113], v[164:167], v[172:175], v[110:113]
	v_mfma_f32_16x16x32_bf16 v[98:101], v[152:155], v[180:183], v[98:101]
	v_mfma_f32_16x16x32_bf16 v[94:97], v[164:167], v[180:183], v[94:97]
	v_mfma_f32_16x16x32_bf16 v[82:85], v[152:155], v[204:207], v[82:85]
	v_mfma_f32_16x16x32_bf16 v[78:81], v[164:167], v[204:207], v[78:81]
	v_mfma_f32_16x16x32_bf16 v[70:73], v[152:155], v[212:215], v[70:73]
	v_mfma_f32_16x16x32_bf16 v[66:69], v[164:167], v[212:215], v[66:69]
	v_mfma_f32_16x16x32_bf16 v[114:117], v[160:163], v[176:179], v[114:117]
	v_mfma_f32_16x16x32_bf16 v[110:113], v[168:171], v[176:179], v[110:113]
	v_mfma_f32_16x16x32_bf16 v[98:101], v[160:163], v[200:203], v[98:101]
	v_mfma_f32_16x16x32_bf16 v[94:97], v[168:171], v[200:203], v[94:97]
	v_mfma_f32_16x16x32_bf16 v[82:85], v[160:163], v[208:211], v[82:85]
	v_mfma_f32_16x16x32_bf16 v[78:81], v[168:171], v[208:211], v[78:81]
	v_mfma_f32_16x16x32_bf16 v[70:73], v[160:163], v[216:219], v[70:73]
	v_mfma_f32_16x16x32_bf16 v[66:69], v[168:171], v[216:219], v[66:69]
	s_barrier
	s_add_i32 s46, s68, s55
	s_add_i32 m0, s46, 0xffffff80
	ds_read_b128 v[172:175], v159 offset:49152
	ds_read_b128 v[176:179], v159 offset:50176
	ds_read_b128 v[180:183], v159 offset:51200
	ds_read_b128 v[200:203], v159 offset:52224
	ds_read_b128 v[204:207], v159 offset:53248
	ds_read_b128 v[208:211], v159 offset:54272
	ds_read_b128 v[212:215], v159 offset:55296
	ds_read_b128 v[216:219], v159 offset:56320
	global_load_lds_dwordx4 v0, s[50:51] offset:128
	s_add_i32 m0, s46, 0x2000
	s_add_u32 s46, s50, 0x200080
	v_lshl_add_u64 v[184:185], v[192:193], 0, s[96:97]
	s_addc_u32 s47, s51, 0
	s_add_i32 s50, s69, s55
	global_load_lds_dwordx4 v[184:185], off
	s_mov_b32 m0, s50
	s_nop 0
	global_load_lds_dwordx4 v0, s[46:47]
	s_add_i32 m0, s50, 0x2000
	s_nop 0
	global_load_lds_dwordx4 v142, s[46:47]
	s_add_i32 m0, s60, 0xffffff80
	s_nop 0
	global_load_lds_dwordx4 v0, s[52:53] offset:128
	s_add_i32 m0, s61, 0xffffff80
	s_nop 0
	global_load_lds_dwordx4 v142, s[52:53] offset:128
	s_waitcnt vmcnt(8)
	s_waitcnt lgkmcnt(0)
	s_barrier
	s_waitcnt lgkmcnt(0)
	v_mfma_f32_16x16x32_bf16 v[62:65], v[130:133], v[172:175], v[62:65]
	v_mfma_f32_16x16x32_bf16 v[58:61], v[138:141], v[172:175], v[58:61]
	v_mfma_f32_16x16x32_bf16 v[54:57], v[130:133], v[180:183], v[54:57]
	v_mfma_f32_16x16x32_bf16 v[42:45], v[138:141], v[180:183], v[42:45]
	s_add_i32 s67, s67, 2
	s_add_u32 s65, s65, 0x100
	s_addc_u32 s66, s66, 0
	s_mov_b64 s[46:47], s[48:49]
	s_add_u32 s48, s46, 0x100
	s_addc_u32 s49, s47, 0
	s_add_i32 s68, 0, 0x10000
	s_cmpk_eq_i32 s67, 0x7c
	s_cselect_b32 s53, s17, s49
	s_cselect_b32 s52, s21, s48
	s_cselect_b32 s51, s15, s66
	s_cselect_b32 s50, s64, s65
	s_add_i32 s69, 0, 0x14000
	v_mfma_f32_16x16x32_bf16 v[38:41], v[130:133], v[204:207], v[38:41]
	v_mfma_f32_16x16x32_bf16 v[26:29], v[138:141], v[204:207], v[26:29]
	v_mfma_f32_16x16x32_bf16 v[22:25], v[130:133], v[212:215], v[22:25]
	v_mfma_f32_16x16x32_bf16 v[10:13], v[138:141], v[212:215], v[10:13]
	v_mfma_f32_16x16x32_bf16 v[62:65], v[134:137], v[176:179], v[62:65]
	v_mfma_f32_16x16x32_bf16 v[58:61], v[148:151], v[176:179], v[58:61]
	v_mfma_f32_16x16x32_bf16 v[54:57], v[134:137], v[200:203], v[54:57]
	v_mfma_f32_16x16x32_bf16 v[42:45], v[148:151], v[200:203], v[42:45]
	v_mfma_f32_16x16x32_bf16 v[38:41], v[134:137], v[208:211], v[38:41]
	v_mfma_f32_16x16x32_bf16 v[26:29], v[148:151], v[208:211], v[26:29]
	v_mfma_f32_16x16x32_bf16 v[22:25], v[134:137], v[216:219], v[22:25]
	v_mfma_f32_16x16x32_bf16 v[10:13], v[148:151], v[216:219], v[10:13]
	v_mfma_f32_16x16x32_bf16 v[50:53], v[152:155], v[172:175], v[50:53]
	v_mfma_f32_16x16x32_bf16 v[46:49], v[164:167], v[172:175], v[46:49]
	v_mfma_f32_16x16x32_bf16 v[34:37], v[152:155], v[180:183], v[34:37]
	v_mfma_f32_16x16x32_bf16 v[30:33], v[164:167], v[180:183], v[30:33]
	v_mfma_f32_16x16x32_bf16 v[18:21], v[152:155], v[204:207], v[18:21]
	v_mfma_f32_16x16x32_bf16 v[14:17], v[164:167], v[204:207], v[14:17]
	v_mfma_f32_16x16x32_bf16 v[6:9], v[152:155], v[212:215], v[6:9]
	v_mfma_f32_16x16x32_bf16 v[2:5], v[164:167], v[212:215], v[2:5]
	v_mfma_f32_16x16x32_bf16 v[50:53], v[160:163], v[176:179], v[50:53]
	v_mfma_f32_16x16x32_bf16 v[46:49], v[168:171], v[176:179], v[46:49]
	v_mfma_f32_16x16x32_bf16 v[34:37], v[160:163], v[200:203], v[34:37]
	v_mfma_f32_16x16x32_bf16 v[30:33], v[168:171], v[200:203], v[30:33]
	v_mfma_f32_16x16x32_bf16 v[18:21], v[160:163], v[208:211], v[18:21]
	v_mfma_f32_16x16x32_bf16 v[14:17], v[168:171], v[208:211], v[14:17]
	v_mfma_f32_16x16x32_bf16 v[6:9], v[160:163], v[216:219], v[6:9]
	v_mfma_f32_16x16x32_bf16 v[2:5], v[168:171], v[216:219], v[2:5]
	s_barrier
	s_cmpk_gt_u32 s67, 0x7d
	s_cbranch_scc0 .LBB0_359
	s_andn2_b64 vcc, s[12:13], s[40:41]
	s_cbranch_vccz .LBB0_362
	s_barrier
